# QKV epilogue on the accumulator layout: per-head RMS via in-lane partial sums + 16-lane DPP tree, gain/scale in registers, two 32-row passes through the LDS slab
# speedup vs baseline: 1.0690x; 1.0344x over previous
; DI float shx(float v, int mask, int lane) { return __int_as_float(__builtin_amdgcn_ds_bpermute((lane ^ mask) << 2, __float_as_int(v))); }
; DI int crow(int i, int hh) { return (i & 3) + 8 * (i >> 2) + 4 * hh; }
; DI void epi_slab(const GemmCfg c, const f32x16 (&acc)[4], float* sW, const float* rss, const size_t row0, const int g, const int lane,
;                  float* const g_h, u16* const g_hb, float* const g_out, const int final_out) {
;   int ln_ = lane;
;   asm volatile("" : "+v"(ln_));
;   const int l31 = ln_ & 31, hh = ln_ >> 5;
; #pragma unroll
;   for (int nb = 0; nb < 4; ++nb)
; #pragma unroll
;     for (int i = 0; i < 16; ++i) sW[crow(i, hh) * 132 + nb * 32 + l31] = acc[nb][i];
;   asm volatile("s_waitcnt lgkmcnt(0)" ::: "memory");
;   const int K = c.K;
;   const float invK = 1.0f / (float)K;
;   if (c.epi == EPI_SWIGLU) {
;     ...
;       if (c.epi == EPI_QKV) {
;         f32x4 x = v * rs;
;         float s = x[0] * x[0] + x[1] * x[1] + x[2] * x[2] + x[3] * x[3];
;         s += shx(s, 1, ln_); s += shx(s, 2, ln_); s += shx(s, 4, ln_); s += shx(s, 8, ln_);
;         if (g < c.nk_end) {
;           const float r2 = rsqrtf(s * (1.f / 64.f) + 1e-6f) * (g < 8 ? 0.125f * LOG2E : 1.f);
;           f32x4 gn = *(const f32x4*)(c.gain + (g < 8 ? 0 : 64) + (c4 & 63));
.LBB0_124:
	s_ashr_i32 s79, s78, 31
	s_lshl_b64 s[4:5], s[78:79], 8
	s_add_u32 s6, s4, s86
	s_addc_u32 s7, s5, s87
	s_lshl_b32 s1, s49, 1
	s_or_b32 s8, s1, s75
	s_lshl_b32 s64, s8, 7
	s_cmp_gt_i32 s8, 1
	s_cselect_b64 s[84:85], -1, 0
	s_cmp_gt_u32 s1, 3
	s_cselect_b64 s[26:27], -1, 0
	s_cmp_eq_u32 s8, 4
	s_cselect_b64 s[70:71], -1, 0
	s_cmp_lt_i32 s8, s20
	s_cselect_b64 s[72:73], -1, 0
	s_cmp_lt_i32 s8, 8
	s_cselect_b64 vcc, -1, 0
	v_mov_b32_e32 v128, 0x3e38aa3b
	v_cndmask_b32_e32 v130, 1.0, v128, vcc
	s_and_b64 s[8:9], vcc, exec
	s_waitcnt lgkmcnt(0)
	v_mov_b64_e32 v[128:129], 0x4080
	s_cselect_b32 s8, 0, 0x100
	v_cmp_lt_u64_e64 s[44:45], s[6:7], v[128:129]
	v_mov_b64_e32 v[128:129], 0x407f
	s_add_u32 s58, s66, s8
	v_cmp_gt_u64_e32 vcc, s[6:7], v[128:129]
	s_addc_u32 s59, s67, 0
	s_barrier
	s_cbranch_vccnz .LBB0_279
	s_cmp_eq_u32 s52, 2
	s_cbranch_scc1 .Lqkv2
	s_cmp_eq_u32 s52, 0
	s_cbranch_scc1 .Lswg2
	v_mov_b32_e32 v131, v185
	s_movk_i32 s8, 0x210
	v_ashrrev_i32_e32 v128, 5, v131
	v_and_b32_e32 v132, 31, v131
	v_mul_lo_u32 v133, v128, s8
	v_lshlrev_b32_e32 v129, 2, v132
	v_lshlrev_b32_e32 v134, 2, v133
	v_add3_u32 v129, s53, v129, v134
	v_lshrrev_b32_e32 v242, 4, v131
	v_mul_u32_u24_e32 v242, 0x840, v242
	v_and_b32_e32 v243, 15, v131
	v_lshl_add_u32 v242, v243, 2, v242
	v_add_u32_e32 v234, s53, v242
	v_add_u32_e32 v235, 0x210, v234
	v_add_u32_e32 v236, 0x420, v234
	v_add_u32_e32 v237, 0x630, v234
	v_add_u32_e32 v238, 0x2100, v234
	v_add_u32_e32 v239, 0x2310, v234
	v_add_u32_e32 v240, 0x2520, v234
	v_add_u32_e32 v241, 0x2730, v234
	ds_write2_b32 v234, v64, v68 offset1:16
	ds_write2_b32 v234, v72, v76 offset0:32 offset1:48
	ds_write2_b32 v234, v80, v84 offset0:64 offset1:80
	ds_write2_b32 v234, v88, v92 offset0:96 offset1:112
	ds_write2_b32 v235, v65, v69 offset1:16
	ds_write2_b32 v235, v73, v77 offset0:32 offset1:48
	ds_write2_b32 v235, v81, v85 offset0:64 offset1:80
	ds_write2_b32 v235, v89, v93 offset0:96 offset1:112
	ds_write2_b32 v236, v66, v70 offset1:16
	ds_write2_b32 v236, v74, v78 offset0:32 offset1:48
	ds_write2_b32 v236, v82, v86 offset0:64 offset1:80
	ds_write2_b32 v236, v90, v94 offset0:96 offset1:112
	ds_write2_b32 v237, v67, v71 offset1:16
	ds_write2_b32 v237, v75, v79 offset0:32 offset1:48
	ds_write2_b32 v237, v83, v87 offset0:64 offset1:80
	ds_write2_b32 v237, v91, v95 offset0:96 offset1:112
	ds_write2_b32 v238, v96, v100 offset1:16
	ds_write2_b32 v238, v104, v108 offset0:32 offset1:48
	ds_write2_b32 v238, v112, v116 offset0:64 offset1:80
	ds_write2_b32 v238, v120, v124 offset0:96 offset1:112
	ds_write2_b32 v239, v97, v101 offset1:16
	ds_write2_b32 v239, v105, v109 offset0:32 offset1:48
	ds_write2_b32 v239, v113, v117 offset0:64 offset1:80
	ds_write2_b32 v239, v121, v125 offset0:96 offset1:112
	ds_write2_b32 v240, v98, v102 offset1:16
	ds_write2_b32 v240, v106, v110 offset0:32 offset1:48
	ds_write2_b32 v240, v114, v118 offset0:64 offset1:80
	ds_write2_b32 v240, v122, v126 offset0:96 offset1:112
	ds_write2_b32 v241, v99, v103 offset1:16
	ds_write2_b32 v241, v107, v111 offset0:32 offset1:48
	ds_write2_b32 v241, v115, v119 offset0:64 offset1:80
	ds_write2_b32 v241, v123, v127 offset0:96 offset1:112
	v_add_u32_e32 v64, 0x3800, v129
	v_add_u32_e32 v65, 0x1000, v129
	v_add_u32_e32 v66, 0x1400, v129
	v_add_u32_e32 v67, 0x2000, v129
	v_add_u32_e32 v68, 0x2400, v129
	v_add_u32_e32 v70, 0x3400, v129
	v_add_u32_e32 v69, 0x3000, v129
	v_add_u32_e32 v71, 0x3600, v129
	s_waitcnt lgkmcnt(0)
	s_mov_b64 s[22:23], -1
	s_mov_b64 s[50:51], 0
	s_cmp_lt_i32 s52, 1
	s_mov_b64 s[14:15], 0
	s_cbranch_scc1 .LBB0_272
	s_cmp_eq_u32 s52, 1
	s_mov_b64 s[14:15], -1
	s_cbranch_scc0 .LBB0_192
; DI void epi_slab(const GemmCfg c, const f32x16 (&acc)[4], float* sW, const float* rss, const size_t row0, const int g, const int lane,
;                  float* const g_h, u16* const g_hb, float* const g_out, const int final_out) {
;     ...
;   } else if (c.epi == EPI_RESID) {
;     const int c4 = l31 * 4;
;     const int col = g * 128 + c4;
;     const float sc = (K == DFF ? 0.5f : 1.f);
; #pragma unroll
;     for (int hb_ = 0; hb_ < 2; ++hb_) {
;       f32x4 hv[8];
; #pragma unroll
;       for (int i8 = 0; i8 < 8; ++i8) hv[i8] = *(const f32x4*)(g_h + (row0 + hh + 2 * (hb_ * 8 + i8)) * D + col);
; #pragma unroll
;       for (int i8 = 0; i8 < 8; ++i8) {
;         const int r = hh + 2 * (hb_ * 8 + i8);
;         const size_t row = row0 + r;
;         f32x4 v = *(const f32x4*)(sW + r * 132 + c4);
;         f32x4 o = hv[i8] + v * sc;
;         *(f32x4*)(g_h + row * D + col) = o;
;         *(u32x2*)(g_hb + row * D + col) = MK2(pack2(o[0], o[1]), pack2(o[2], o[3]));
;         if (final_out) {
;           const int b = (int)(row / T), t = (int)(row % T);
;           if (t >= 16) *(f32x4*)(g_out + ((size_t)b * 2048 + (t - 16)) * D + col) = o;
;         }
;       }
	v_lshl_or_b32 v98, v132, 2, s64
	v_ashrrev_i32_e32 v129, 31, v128
	v_ashrrev_i32_e32 v99, 31, v98
	v_readlane_b32 s8, v254, 60
	v_lshl_add_u64 v[104:105], s[6:7], 0, v[128:129]
	v_lshlrev_b64 v[106:107], 2, v[98:99]
	v_readlane_b32 s9, v254, 61
	v_lshlrev_b64 v[64:65], 12, v[104:105]
	v_lshl_add_u32 v108, v132, 4, s53
	v_lshl_add_u64 v[96:97], s[8:9], 0, v[106:107]
	v_lshl_add_u64 v[102:103], v[96:97], 0, v[64:65]
	s_movk_i32 s8, 0x2000
	v_add_co_u32_e32 v64, vcc, s8, v102
	s_movk_i32 s8, 0x4000
	s_nop 0
	v_addc_co_u32_e32 v65, vcc, 0, v103, vcc
	global_load_dwordx4 v[92:95], v[102:103], off
	global_load_dwordx4 v[88:91], v[64:65], off
	v_add_co_u32_e32 v64, vcc, s8, v102
	s_movk_i32 s8, 0x6000
	s_nop 0
	v_addc_co_u32_e32 v65, vcc, 0, v103, vcc
	v_add_co_u32_e32 v66, vcc, s8, v102
	s_mov_b32 s8, 0x8000
	s_nop 0
	v_addc_co_u32_e32 v67, vcc, 0, v103, vcc
	global_load_dwordx4 v[84:87], v[64:65], off
	global_load_dwordx4 v[80:83], v[66:67], off
	v_add_co_u32_e32 v64, vcc, s8, v102
	s_mov_b32 s8, 0xa000
	s_nop 0
	v_addc_co_u32_e32 v65, vcc, 0, v103, vcc
	v_add_co_u32_e32 v66, vcc, s8, v102
	s_mov_b32 s8, 0xc000
	s_nop 0
	v_addc_co_u32_e32 v67, vcc, 0, v103, vcc
	global_load_dwordx4 v[76:79], v[64:65], off
	global_load_dwordx4 v[72:75], v[66:67], off
	v_add_co_u32_e32 v64, vcc, s8, v102
	s_mov_b32 s8, 0xe000
	s_nop 0
	v_addc_co_u32_e32 v65, vcc, 0, v103, vcc
	v_add_co_u32_e32 v66, vcc, s8, v102
	v_add_u32_e32 v100, v108, v133
	s_nop 0
	v_addc_co_u32_e32 v67, vcc, 0, v103, vcc
	global_load_dwordx4 v[68:71], v[64:65], off
	s_nop 0
	global_load_dwordx4 v[64:67], v[66:67], off
	v_readlane_b32 s8, v255, 3
	ds_read_b128 v[110:113], v100
	v_readlane_b32 s9, v255, 4
	v_mov_b32_e32 v171, v170
	s_waitcnt vmcnt(7) lgkmcnt(0)
	v_pk_fma_f32 v[94:95], v[170:171], v[112:113], v[94:95]
	v_lshl_add_u64 v[100:101], v[98:99], 1, s[8:9]
	v_mov_b32_e32 v148, 0x11f69000
	v_mov_b32_e32 v149, 0
	v_lshl_add_u64 v[146:147], v[148:149], 0, s[8:9]
	v_lshrrev_b32_e32 v148, 6, v98
	v_lshlrev_b32_e32 v148, 2, v148
	v_lshl_add_u64 v[146:147], v[146:147], 0, v[148:149]
	v_mov_b32_e32 v143, 0
	v_readlane_b32 s8, v252, 47
	v_readlane_b32 s9, v252, 48
	v_readlane_b32 s8, v255, 13
	v_readlane_b32 s9, v255, 14
	v_readlane_b32 s22, v252, 61
	v_readlane_b32 s23, v252, 62
	v_pk_fma_f32 v[92:93], v[172:173], v[110:111], v[92:93]
	v_lshlrev_b64 v[110:111], 11, v[104:105]
	v_cndmask_b32_e64 v109, 0, 1, s[8:9]
	v_lshl_add_u64 v[98:99], s[22:23], 0, v[106:107]
	v_cvt_pk_bf16_f32 v106, v92, v93
	v_cvt_pk_bf16_f32 v107, v94, v95
	v_lshrrev_b32_e32 v142, 5, v110
	v_lshl_add_u64 v[110:111], v[100:101], 0, v[110:111]
	v_cmp_ne_u32_e64 s[46:47], 1, v109
	s_andn2_b64 vcc, exec, s[8:9]
	v_readlane_b32 s10, v252, 49
	v_readlane_b32 s11, v252, 50
	v_readlane_b32 s12, v252, 51
	v_readlane_b32 s13, v252, 52
	v_readlane_b32 s14, v252, 53
	v_readlane_b32 s15, v252, 54
	v_readlane_b32 s16, v252, 55
	v_readlane_b32 s17, v252, 56
	v_readlane_b32 s18, v252, 57
	v_readlane_b32 s19, v252, 58
	v_readlane_b32 s20, v252, 59
	v_readlane_b32 s21, v252, 60
	global_store_dwordx4 v[102:103], v[92:95], off
	global_store_dwordx2 v[110:111], v[106:107], off
	v_mov_b32_e32 v141, 0
	v_dot2c_f32_bf16_e32 v141, v106, v106
	v_dot2c_f32_bf16_e32 v141, v107, v107
	s_nop 4
	v_add_f32_dpp v141, v141, v141 quad_perm:[1,0,3,2] row_mask:0xf bank_mask:0xf
	s_nop 1
	v_add_f32_dpp v141, v141, v141 quad_perm:[2,3,0,1] row_mask:0xf bank_mask:0xf
	s_nop 1
	v_add_f32_dpp v141, v141, v141 row_half_mirror row_mask:0xf bank_mask:0xf
	s_nop 1
	v_add_f32_dpp v141, v141, v141 row_mirror row_mask:0xf bank_mask:0xf
	v_lshl_add_u64 v[144:145], v[142:143], 0, v[146:147]
	global_store_dword v[144:145], v141, off
	s_cbranch_vccnz .LBB0_131
	s_mov_b32 s8, 0xe03f80ff
	v_mul_hi_u32 v164, v104, s8
	v_mad_u64_u32 v[106:107], s[14:15], v105, s8, v[164:165]
	v_mov_b32_e32 v164, v107
	v_mov_b32_e32 v107, v165
	s_mov_b32 s8, 0xfe03f80f
	v_mad_u64_u32 v[106:107], s[14:15], v104, s8, v[106:107]
	v_mov_b32_e32 v106, v107
	v_mov_b32_e32 v107, v165
	v_lshl_add_u64 v[106:107], v[164:165], 0, v[106:107]
	v_mad_u64_u32 v[106:107], s[14:15], v105, s8, v[106:107]
	v_alignbit_b32 v109, v107, v106, 11
	s_movk_i32 s8, 0x810
	v_mad_u64_u32 v[110:111], s[14:15], v109, s8, 0
	v_lshrrev_b32_e32 v109, 11, v107
	v_mad_u32_u24 v109, v109, s8, v111
	v_sub_co_u32_e32 v104, vcc, v104, v110
	s_nop 1
	v_subb_co_u32_e32 v105, vcc, v105, v109, vcc
	v_cmp_lt_u64_e32 vcc, 15, v[104:105]
	s_and_saveexec_b64 s[14:15], vcc
	s_cbranch_execz .LBB0_130
	v_lshrrev_b64 v[106:107], 11, v[106:107]
	v_mov_b32_e32 v110, v165
	v_mov_b32_e32 v111, v106
	v_ashrrev_i64 v[106:107], 21, v[110:111]
	v_add_u32_e32 v164, -16, v104
	v_lshl_add_u64 v[104:105], v[106:107], 0, v[164:165]
	v_lshlrev_b64 v[104:105], 12, v[104:105]
	v_lshl_add_u64 v[104:105], v[98:99], 0, v[104:105]
	global_store_dwordx4 v[104:105], v[92:95], off

; DI float shx(float v, int mask, int lane) { return __int_as_float(__builtin_amdgcn_ds_bpermute((lane ^ mask) << 2, __float_as_int(v))); }
; DI void epi_slab(const GemmCfg c, const f32x16 (&acc)[4], float* sW, const float* rss, const size_t row0, const int g, const int lane,
;                  float* const g_h, u16* const g_hb, float* const g_out, const int final_out) {
;     ...
;     const int c4 = l31 * 4;
;     const int col = g * 128 + c4;
; #pragma unroll 2
;     for (int it = 0; it < 16; ++it) {
;       const int r = hh + 2 * it;
;       const size_t row = row0 + r;
;       f32x4 v = *(const f32x4*)(sW + r * 132 + c4);
;       const float rs = c.use_rs ? rsqrtf(rss[r] * invK + 1e-6f) : 1.f;
;       if (c.epi == EPI_QKV) {
;         f32x4 x = v * rs;
;         float s = x[0] * x[0] + x[1] * x[1] + x[2] * x[2] + x[3] * x[3];
;         s += shx(s, 1, ln_); s += shx(s, 2, ln_); s += shx(s, 4, ln_); s += shx(s, 8, ln_);
;         if (g < c.nk_end) {
;           const float r2 = rsqrtf(s * (1.f / 64.f) + 1e-6f) * (g < 8 ? 0.125f * LOG2E : 1.f);
;           f32x4 gn = *(const f32x4*)(c.gain + (g < 8 ? 0 : 64) + (c4 & 63));
;           x = x * gn * r2;
.Lqkv2:
	v_and_b32_e32 v222, 15, v185
	v_lshrrev_b32_e32 v223, 4, v185
	s_lshl_b32 s4, s86, 2
	s_add_i32 s4, s4, 0x24000
	v_lshl_add_u32 v224, v223, 4, s4
	ds_read_b128 v[226:229], v224
	ds_read_b128 v[230:233], v224 offset:64
	ds_read_b128 v[234:237], v224 offset:128
	ds_read_b128 v[238:241], v224 offset:192
	v_lshlrev_b32_e32 v206, 2, v222
	global_load_dword v132, v206, s[58:59]
	global_load_dword v134, v206, s[58:59] offset:64
	global_load_dword v136, v206, s[58:59] offset:128
	global_load_dword v138, v206, s[58:59] offset:192
	v_mul_u32_u24_e32 v198, 0x840, v223
	v_lshl_add_u32 v198, v222, 2, v198
	v_add_u32_e32 v198, s53, v198
	v_add_u32_e32 v199, 0x420, v198
	v_add_u32_e32 v200, 0x2100, v198
	v_add_u32_e32 v201, 0x2520, v198
	v_lshrrev_b32_e32 v202, 5, v185
	v_and_b32_e32 v206, 31, v185
	v_mul_u32_u24_e32 v204, 0x210, v202
	v_lshl_add_u32 v204, v206, 4, v204
	v_add_u32_e32 v205, s53, v204
	v_mov_b32_e32 v250, v205
	v_add_u32_e32 v204, s6, v202
	v_mul_lo_u32 v204, v204, s92
	v_lshl_add_u32 v206, v206, 2, s64
	v_lshl_add_u32 v204, v206, 1, v204
	v_mov_b32_e32 v205, 0
	v_lshl_add_u64 v[204:205], v[204:205], 0, s[56:57]
	v_mov_b32_e32 v202, v250
	v_mov_b32_e32 v250, 0x3c800000
	s_lshl_b32 s4, s92, 1
	s_mov_b64 s[8:9], 0
	s_waitcnt lgkmcnt(0)
	v_fmaak_f32 v226, v191, v226, 0x358637bd
	v_fmaak_f32 v227, v191, v227, 0x358637bd
	v_cmp_gt_f32_e32 vcc, s33, v226
	v_cmp_gt_f32_e64 s[14:15], s33, v227
	v_mul_f32_e32 v224, 0x4b800000, v226
	v_mul_f32_e32 v225, 0x4b800000, v227
	v_cndmask_b32_e32 v226, v226, v224, vcc
	v_cndmask_b32_e64 v227, v227, v225, s[14:15]
	v_rsq_f32_e32 v226, v226
	v_rsq_f32_e32 v227, v227
	s_nop 0
	v_mul_f32_e32 v224, 0x45800000, v226
	v_mul_f32_e32 v225, 0x45800000, v227
	v_cndmask_b32_e32 v226, v226, v224, vcc
	v_cndmask_b32_e64 v227, v227, v225, s[14:15]
	v_fmaak_f32 v228, v191, v228, 0x358637bd
	v_fmaak_f32 v229, v191, v229, 0x358637bd
	v_cmp_gt_f32_e32 vcc, s33, v228
	v_cmp_gt_f32_e64 s[14:15], s33, v229
	v_mul_f32_e32 v224, 0x4b800000, v228
	v_mul_f32_e32 v225, 0x4b800000, v229
	v_cndmask_b32_e32 v228, v228, v224, vcc
	v_cndmask_b32_e64 v229, v229, v225, s[14:15]
	v_rsq_f32_e32 v228, v228
	v_rsq_f32_e32 v229, v229
	s_nop 0
	v_mul_f32_e32 v224, 0x45800000, v228
	v_mul_f32_e32 v225, 0x45800000, v229
	v_cndmask_b32_e32 v228, v228, v224, vcc
	v_cndmask_b32_e64 v229, v229, v225, s[14:15]
	v_fmaak_f32 v230, v191, v230, 0x358637bd
	v_fmaak_f32 v231, v191, v231, 0x358637bd
	v_cmp_gt_f32_e32 vcc, s33, v230
	v_cmp_gt_f32_e64 s[14:15], s33, v231
	v_mul_f32_e32 v224, 0x4b800000, v230
	v_mul_f32_e32 v225, 0x4b800000, v231
	v_cndmask_b32_e32 v230, v230, v224, vcc
	v_cndmask_b32_e64 v231, v231, v225, s[14:15]
	v_rsq_f32_e32 v230, v230
	v_rsq_f32_e32 v231, v231
	s_nop 0
	v_mul_f32_e32 v224, 0x45800000, v230
	v_mul_f32_e32 v225, 0x45800000, v231
	v_cndmask_b32_e32 v230, v230, v224, vcc
	v_cndmask_b32_e64 v231, v231, v225, s[14:15]
	v_fmaak_f32 v232, v191, v232, 0x358637bd
	v_fmaak_f32 v233, v191, v233, 0x358637bd
	v_cmp_gt_f32_e32 vcc, s33, v232
	v_cmp_gt_f32_e64 s[14:15], s33, v233
	v_mul_f32_e32 v224, 0x4b800000, v232
	v_mul_f32_e32 v225, 0x4b800000, v233
	v_cndmask_b32_e32 v232, v232, v224, vcc
	v_cndmask_b32_e64 v233, v233, v225, s[14:15]
	v_rsq_f32_e32 v232, v232
	v_rsq_f32_e32 v233, v233
	s_nop 0
	v_mul_f32_e32 v224, 0x45800000, v232
	v_mul_f32_e32 v225, 0x45800000, v233
	v_cndmask_b32_e32 v232, v232, v224, vcc
	v_cndmask_b32_e64 v233, v233, v225, s[14:15]
	v_fmaak_f32 v234, v191, v234, 0x358637bd
	v_fmaak_f32 v235, v191, v235, 0x358637bd
	v_cmp_gt_f32_e32 vcc, s33, v234
	v_cmp_gt_f32_e64 s[14:15], s33, v235
	v_mul_f32_e32 v224, 0x4b800000, v234
	v_mul_f32_e32 v225, 0x4b800000, v235
	v_cndmask_b32_e32 v234, v234, v224, vcc
	v_cndmask_b32_e64 v235, v235, v225, s[14:15]
	v_rsq_f32_e32 v234, v234
	v_rsq_f32_e32 v235, v235
	s_nop 0
	v_mul_f32_e32 v224, 0x45800000, v234
	v_mul_f32_e32 v225, 0x45800000, v235
	v_cndmask_b32_e32 v234, v234, v224, vcc
	v_cndmask_b32_e64 v235, v235, v225, s[14:15]
	v_fmaak_f32 v236, v191, v236, 0x358637bd
	v_fmaak_f32 v237, v191, v237, 0x358637bd
	v_cmp_gt_f32_e32 vcc, s33, v236
	v_cmp_gt_f32_e64 s[14:15], s33, v237
	v_mul_f32_e32 v224, 0x4b800000, v236
	v_mul_f32_e32 v225, 0x4b800000, v237
	v_cndmask_b32_e32 v236, v236, v224, vcc
	v_cndmask_b32_e64 v237, v237, v225, s[14:15]
	v_rsq_f32_e32 v236, v236
	v_rsq_f32_e32 v237, v237
	s_nop 0
	v_mul_f32_e32 v224, 0x45800000, v236
	v_mul_f32_e32 v225, 0x45800000, v237
	v_cndmask_b32_e32 v236, v236, v224, vcc
	v_cndmask_b32_e64 v237, v237, v225, s[14:15]
	v_fmaak_f32 v238, v191, v238, 0x358637bd
	v_fmaak_f32 v239, v191, v239, 0x358637bd
	v_cmp_gt_f32_e32 vcc, s33, v238
	v_cmp_gt_f32_e64 s[14:15], s33, v239
	v_mul_f32_e32 v224, 0x4b800000, v238
	v_mul_f32_e32 v225, 0x4b800000, v239
	v_cndmask_b32_e32 v238, v238, v224, vcc
	v_cndmask_b32_e64 v239, v239, v225, s[14:15]
	v_rsq_f32_e32 v238, v238
	v_rsq_f32_e32 v239, v239
	s_nop 0
	v_mul_f32_e32 v224, 0x45800000, v238
	v_mul_f32_e32 v225, 0x45800000, v239
	v_cndmask_b32_e32 v238, v238, v224, vcc
	v_cndmask_b32_e64 v239, v239, v225, s[14:15]
	v_fmaak_f32 v240, v191, v240, 0x358637bd
	v_fmaak_f32 v241, v191, v241, 0x358637bd
	v_cmp_gt_f32_e32 vcc, s33, v240
	v_cmp_gt_f32_e64 s[14:15], s33, v241
	v_mul_f32_e32 v224, 0x4b800000, v240
	v_mul_f32_e32 v225, 0x4b800000, v241
	v_cndmask_b32_e32 v240, v240, v224, vcc
	v_cndmask_b32_e64 v241, v241, v225, s[14:15]
	v_rsq_f32_e32 v240, v240
	v_rsq_f32_e32 v241, v241
	s_nop 0
	v_mul_f32_e32 v224, 0x45800000, v240
	v_mul_f32_e32 v225, 0x45800000, v241
	v_cndmask_b32_e32 v240, v240, v224, vcc
	v_cndmask_b32_e64 v241, v241, v225, s[14:15]
	s_waitcnt vmcnt(0)
	v_pk_mul_f32 v[64:65], v[64:65], v[226:227]
	v_pk_mul_f32 v[66:67], v[66:67], v[228:229]
	v_pk_mul_f32 v[68:69], v[68:69], v[226:227]
	v_pk_mul_f32 v[70:71], v[70:71], v[228:229]
	v_pk_mul_f32 v[72:73], v[72:73], v[226:227]
	v_pk_mul_f32 v[74:75], v[74:75], v[228:229]
	v_pk_mul_f32 v[76:77], v[76:77], v[226:227]
	v_pk_mul_f32 v[78:79], v[78:79], v[228:229]
	v_pk_mul_f32 v[80:81], v[80:81], v[226:227]
	v_pk_mul_f32 v[82:83], v[82:83], v[228:229]
	v_pk_mul_f32 v[84:85], v[84:85], v[226:227]
	v_pk_mul_f32 v[86:87], v[86:87], v[228:229]
	v_pk_mul_f32 v[88:89], v[88:89], v[226:227]
	v_pk_mul_f32 v[90:91], v[90:91], v[228:229]
	v_pk_mul_f32 v[92:93], v[92:93], v[226:227]
	v_pk_mul_f32 v[94:95], v[94:95], v[228:229]
	s_and_b64 vcc, exec, s[72:73]
	s_cbranch_vccz .Lqkv2_plain0
; DI float shx(float v, int mask, int lane) { return __int_as_float(__builtin_amdgcn_ds_bpermute((lane ^ mask) << 2, __float_as_int(v))); }
; DI void epi_slab(const GemmCfg c, const f32x16 (&acc)[4], float* sW, const float* rss, const size_t row0, const int g, const int lane,
;                  float* const g_h, u16* const g_hb, float* const g_out, const int final_out) {
;     ...
;       if (c.epi == EPI_QKV) {
;         f32x4 x = v * rs;
;         float s = x[0] * x[0] + x[1] * x[1] + x[2] * x[2] + x[3] * x[3];
;         s += shx(s, 1, ln_); s += shx(s, 2, ln_); s += shx(s, 4, ln_); s += shx(s, 8, ln_);
;         if (g < c.nk_end) {
;           const float r2 = rsqrtf(s * (1.f / 64.f) + 1e-6f) * (g < 8 ? 0.125f * LOG2E : 1.f);
;           f32x4 gn = *(const f32x4*)(c.gain + (g < 8 ? 0 : 64) + (c4 & 63));
;           x = x * gn * r2;
;         }
;         *(u32x2*)(c.o16 + row * c.ldo + col) = MK2(pack2(x[0], x[1]), pack2(x[2], x[3]));
	v_mul_f32_e32 v246, v64, v64
	v_mul_f32_e32 v247, v65, v65
	v_mul_f32_e32 v248, v66, v66
	v_mul_f32_e32 v249, v67, v67
	v_fmac_f32_e32 v246, v68, v68
	v_fmac_f32_e32 v247, v69, v69
	v_fmac_f32_e32 v248, v70, v70
	v_fmac_f32_e32 v249, v71, v71
	v_fmac_f32_e32 v246, v72, v72
	v_fmac_f32_e32 v247, v73, v73
	v_fmac_f32_e32 v248, v74, v74
	v_fmac_f32_e32 v249, v75, v75
	v_fmac_f32_e32 v246, v76, v76
	v_fmac_f32_e32 v247, v77, v77
	v_fmac_f32_e32 v248, v78, v78
	v_fmac_f32_e32 v249, v79, v79
	v_add_f32_dpp v246, v246, v246 quad_perm:[1,0,3,2] row_mask:0xf bank_mask:0xf
	v_add_f32_dpp v247, v247, v247 quad_perm:[1,0,3,2] row_mask:0xf bank_mask:0xf
	v_add_f32_dpp v248, v248, v248 quad_perm:[1,0,3,2] row_mask:0xf bank_mask:0xf
	v_add_f32_dpp v249, v249, v249 quad_perm:[1,0,3,2] row_mask:0xf bank_mask:0xf
	v_add_f32_dpp v246, v246, v246 quad_perm:[2,3,0,1] row_mask:0xf bank_mask:0xf
	v_add_f32_dpp v247, v247, v247 quad_perm:[2,3,0,1] row_mask:0xf bank_mask:0xf
	v_add_f32_dpp v248, v248, v248 quad_perm:[2,3,0,1] row_mask:0xf bank_mask:0xf
	v_add_f32_dpp v249, v249, v249 quad_perm:[2,3,0,1] row_mask:0xf bank_mask:0xf
	v_add_f32_dpp v246, v246, v246 row_half_mirror row_mask:0xf bank_mask:0xf
	v_add_f32_dpp v247, v247, v247 row_half_mirror row_mask:0xf bank_mask:0xf
	v_add_f32_dpp v248, v248, v248 row_half_mirror row_mask:0xf bank_mask:0xf
	v_add_f32_dpp v249, v249, v249 row_half_mirror row_mask:0xf bank_mask:0xf
	v_add_f32_dpp v246, v246, v246 row_mirror row_mask:0xf bank_mask:0xf
	v_add_f32_dpp v247, v247, v247 row_mirror row_mask:0xf bank_mask:0xf
	v_add_f32_dpp v248, v248, v248 row_mirror row_mask:0xf bank_mask:0xf
	v_add_f32_dpp v249, v249, v249 row_mirror row_mask:0xf bank_mask:0xf
	v_fmaak_f32 v246, v250, v246, 0x358637bd
	v_fmaak_f32 v247, v250, v247, 0x358637bd
	v_cmp_gt_f32_e32 vcc, s33, v246
	v_cmp_gt_f32_e64 s[14:15], s33, v247
	v_mul_f32_e32 v224, 0x4b800000, v246
	v_mul_f32_e32 v225, 0x4b800000, v247
	v_cndmask_b32_e32 v246, v246, v224, vcc
	v_cndmask_b32_e64 v247, v247, v225, s[14:15]
	v_rsq_f32_e32 v246, v246
	v_rsq_f32_e32 v247, v247
	s_nop 0
	v_mul_f32_e32 v224, 0x45800000, v246
	v_mul_f32_e32 v225, 0x45800000, v247
	v_cndmask_b32_e32 v246, v246, v224, vcc
	v_cndmask_b32_e64 v247, v247, v225, s[14:15]
	v_mul_f32_e32 v246, v246, v130
	v_mul_f32_e32 v247, v247, v130
	v_fmaak_f32 v248, v250, v248, 0x358637bd
	v_fmaak_f32 v249, v250, v249, 0x358637bd
	v_cmp_gt_f32_e32 vcc, s33, v248
	v_cmp_gt_f32_e64 s[14:15], s33, v249
	v_mul_f32_e32 v224, 0x4b800000, v248
	v_mul_f32_e32 v225, 0x4b800000, v249
	v_cndmask_b32_e32 v248, v248, v224, vcc
	v_cndmask_b32_e64 v249, v249, v225, s[14:15]
	v_rsq_f32_e32 v248, v248
	v_rsq_f32_e32 v249, v249
	s_nop 0
	v_mul_f32_e32 v224, 0x45800000, v248
	v_mul_f32_e32 v225, 0x45800000, v249
	v_cndmask_b32_e32 v248, v248, v224, vcc
	v_cndmask_b32_e64 v249, v249, v225, s[14:15]
	v_mul_f32_e32 v248, v248, v130
	v_mul_f32_e32 v249, v249, v130
	v_pk_mul_f32 v[64:65], v[64:65], v[246:247]
	v_pk_mul_f32 v[66:67], v[66:67], v[248:249]
	v_pk_mul_f32 v[64:65], v[64:65], v[132:133] op_sel_hi:[1,0]
	v_pk_mul_f32 v[66:67], v[66:67], v[132:133] op_sel_hi:[1,0]
	v_pk_mul_f32 v[68:69], v[68:69], v[246:247]
	v_pk_mul_f32 v[70:71], v[70:71], v[248:249]
	v_pk_mul_f32 v[68:69], v[68:69], v[134:135] op_sel_hi:[1,0]
	v_pk_mul_f32 v[70:71], v[70:71], v[134:135] op_sel_hi:[1,0]
	v_pk_mul_f32 v[72:73], v[72:73], v[246:247]
	v_pk_mul_f32 v[74:75], v[74:75], v[248:249]
	v_pk_mul_f32 v[72:73], v[72:73], v[136:137] op_sel_hi:[1,0]
	v_pk_mul_f32 v[74:75], v[74:75], v[136:137] op_sel_hi:[1,0]
	v_pk_mul_f32 v[76:77], v[76:77], v[246:247]
	v_pk_mul_f32 v[78:79], v[78:79], v[248:249]
	v_pk_mul_f32 v[76:77], v[76:77], v[138:139] op_sel_hi:[1,0]
	v_pk_mul_f32 v[78:79], v[78:79], v[138:139] op_sel_hi:[1,0]
	v_mul_f32_e32 v246, v80, v80
	v_mul_f32_e32 v247, v81, v81
	v_mul_f32_e32 v248, v82, v82
	v_mul_f32_e32 v249, v83, v83
	v_fmac_f32_e32 v246, v84, v84
	v_fmac_f32_e32 v247, v85, v85
	v_fmac_f32_e32 v248, v86, v86
	v_fmac_f32_e32 v249, v87, v87
	v_fmac_f32_e32 v246, v88, v88
	v_fmac_f32_e32 v247, v89, v89
	v_fmac_f32_e32 v248, v90, v90
	v_fmac_f32_e32 v249, v91, v91
	v_fmac_f32_e32 v246, v92, v92
	v_fmac_f32_e32 v247, v93, v93
	v_fmac_f32_e32 v248, v94, v94
	v_fmac_f32_e32 v249, v95, v95
	v_add_f32_dpp v246, v246, v246 quad_perm:[1,0,3,2] row_mask:0xf bank_mask:0xf
	v_add_f32_dpp v247, v247, v247 quad_perm:[1,0,3,2] row_mask:0xf bank_mask:0xf
	v_add_f32_dpp v248, v248, v248 quad_perm:[1,0,3,2] row_mask:0xf bank_mask:0xf
	v_add_f32_dpp v249, v249, v249 quad_perm:[1,0,3,2] row_mask:0xf bank_mask:0xf
	v_add_f32_dpp v246, v246, v246 quad_perm:[2,3,0,1] row_mask:0xf bank_mask:0xf
	v_add_f32_dpp v247, v247, v247 quad_perm:[2,3,0,1] row_mask:0xf bank_mask:0xf
	v_add_f32_dpp v248, v248, v248 quad_perm:[2,3,0,1] row_mask:0xf bank_mask:0xf
	v_add_f32_dpp v249, v249, v249 quad_perm:[2,3,0,1] row_mask:0xf bank_mask:0xf
	v_add_f32_dpp v246, v246, v246 row_half_mirror row_mask:0xf bank_mask:0xf
	v_add_f32_dpp v247, v247, v247 row_half_mirror row_mask:0xf bank_mask:0xf
	v_add_f32_dpp v248, v248, v248 row_half_mirror row_mask:0xf bank_mask:0xf
	v_add_f32_dpp v249, v249, v249 row_half_mirror row_mask:0xf bank_mask:0xf
	v_add_f32_dpp v246, v246, v246 row_mirror row_mask:0xf bank_mask:0xf
	v_add_f32_dpp v247, v247, v247 row_mirror row_mask:0xf bank_mask:0xf
	v_add_f32_dpp v248, v248, v248 row_mirror row_mask:0xf bank_mask:0xf
	v_add_f32_dpp v249, v249, v249 row_mirror row_mask:0xf bank_mask:0xf
	v_fmaak_f32 v246, v250, v246, 0x358637bd
	v_fmaak_f32 v247, v250, v247, 0x358637bd
	v_cmp_gt_f32_e32 vcc, s33, v246
	v_cmp_gt_f32_e64 s[14:15], s33, v247
; DI float shx(float v, int mask, int lane) { return __int_as_float(__builtin_amdgcn_ds_bpermute((lane ^ mask) << 2, __float_as_int(v))); }
; DI void epi_slab(const GemmCfg c, const f32x16 (&acc)[4], float* sW, const float* rss, const size_t row0, const int g, const int lane,
;                  float* const g_h, u16* const g_hb, float* const g_out, const int final_out) {
;     ...
;       if (c.epi == EPI_QKV) {
;         f32x4 x = v * rs;
;         float s = x[0] * x[0] + x[1] * x[1] + x[2] * x[2] + x[3] * x[3];
;         s += shx(s, 1, ln_); s += shx(s, 2, ln_); s += shx(s, 4, ln_); s += shx(s, 8, ln_);
;         if (g < c.nk_end) {
;           const float r2 = rsqrtf(s * (1.f / 64.f) + 1e-6f) * (g < 8 ? 0.125f * LOG2E : 1.f);
;           f32x4 gn = *(const f32x4*)(c.gain + (g < 8 ? 0 : 64) + (c4 & 63));
;           x = x * gn * r2;
;         }
;         *(u32x2*)(c.o16 + row * c.ldo + col) = MK2(pack2(x[0], x[1]), pack2(x[2], x[3]));
	v_mul_f32_e32 v224, 0x4b800000, v246
	v_mul_f32_e32 v225, 0x4b800000, v247
	v_cndmask_b32_e32 v246, v246, v224, vcc
	v_cndmask_b32_e64 v247, v247, v225, s[14:15]
	v_rsq_f32_e32 v246, v246
	v_rsq_f32_e32 v247, v247
	s_nop 0
	v_mul_f32_e32 v224, 0x45800000, v246
	v_mul_f32_e32 v225, 0x45800000, v247
	v_cndmask_b32_e32 v246, v246, v224, vcc
	v_cndmask_b32_e64 v247, v247, v225, s[14:15]
	v_mul_f32_e32 v246, v246, v130
	v_mul_f32_e32 v247, v247, v130
	v_fmaak_f32 v248, v250, v248, 0x358637bd
	v_fmaak_f32 v249, v250, v249, 0x358637bd
	v_cmp_gt_f32_e32 vcc, s33, v248
	v_cmp_gt_f32_e64 s[14:15], s33, v249
	v_mul_f32_e32 v224, 0x4b800000, v248
	v_mul_f32_e32 v225, 0x4b800000, v249
	v_cndmask_b32_e32 v248, v248, v224, vcc
	v_cndmask_b32_e64 v249, v249, v225, s[14:15]
	v_rsq_f32_e32 v248, v248
	v_rsq_f32_e32 v249, v249
	s_nop 0
	v_mul_f32_e32 v224, 0x45800000, v248
	v_mul_f32_e32 v225, 0x45800000, v249
	v_cndmask_b32_e32 v248, v248, v224, vcc
	v_cndmask_b32_e64 v249, v249, v225, s[14:15]
	v_mul_f32_e32 v248, v248, v130
	v_mul_f32_e32 v249, v249, v130
	v_pk_mul_f32 v[80:81], v[80:81], v[246:247]
	v_pk_mul_f32 v[82:83], v[82:83], v[248:249]
	v_pk_mul_f32 v[80:81], v[80:81], v[132:133] op_sel_hi:[1,0]
	v_pk_mul_f32 v[82:83], v[82:83], v[132:133] op_sel_hi:[1,0]
	v_pk_mul_f32 v[84:85], v[84:85], v[246:247]
	v_pk_mul_f32 v[86:87], v[86:87], v[248:249]
	v_pk_mul_f32 v[84:85], v[84:85], v[134:135] op_sel_hi:[1,0]
	v_pk_mul_f32 v[86:87], v[86:87], v[134:135] op_sel_hi:[1,0]
	v_pk_mul_f32 v[88:89], v[88:89], v[246:247]
	v_pk_mul_f32 v[90:91], v[90:91], v[248:249]
	v_pk_mul_f32 v[88:89], v[88:89], v[136:137] op_sel_hi:[1,0]
	v_pk_mul_f32 v[90:91], v[90:91], v[136:137] op_sel_hi:[1,0]
	v_pk_mul_f32 v[92:93], v[92:93], v[246:247]
	v_pk_mul_f32 v[94:95], v[94:95], v[248:249]
	v_pk_mul_f32 v[92:93], v[92:93], v[138:139] op_sel_hi:[1,0]
	v_pk_mul_f32 v[94:95], v[94:95], v[138:139] op_sel_hi:[1,0]
.Lqkv2_plain0:
	ds_write2_b32 v198, v64, v65 offset0:0 offset1:132
	ds_write2_b32 v199, v66, v67 offset0:0 offset1:132
	ds_write2_b32 v198, v68, v69 offset0:16 offset1:148
	ds_write2_b32 v199, v70, v71 offset0:16 offset1:148
	ds_write2_b32 v198, v72, v73 offset0:32 offset1:164
	ds_write2_b32 v199, v74, v75 offset0:32 offset1:164
	ds_write2_b32 v198, v76, v77 offset0:48 offset1:180
	ds_write2_b32 v199, v78, v79 offset0:48 offset1:180
	ds_write2_b32 v198, v80, v81 offset0:64 offset1:196
	ds_write2_b32 v199, v82, v83 offset0:64 offset1:196
	ds_write2_b32 v198, v84, v85 offset0:80 offset1:212
	ds_write2_b32 v199, v86, v87 offset0:80 offset1:212
	ds_write2_b32 v198, v88, v89 offset0:96 offset1:228
	ds_write2_b32 v199, v90, v91 offset0:96 offset1:228
	ds_write2_b32 v198, v92, v93 offset0:112 offset1:244
	ds_write2_b32 v199, v94, v95 offset0:112 offset1:244
	v_pk_mul_f32 v[96:97], v[96:97], v[230:231]
	v_pk_mul_f32 v[98:99], v[98:99], v[232:233]
	v_pk_mul_f32 v[100:101], v[100:101], v[230:231]
	v_pk_mul_f32 v[102:103], v[102:103], v[232:233]
	v_pk_mul_f32 v[104:105], v[104:105], v[230:231]
	v_pk_mul_f32 v[106:107], v[106:107], v[232:233]
	v_pk_mul_f32 v[108:109], v[108:109], v[230:231]
	v_pk_mul_f32 v[110:111], v[110:111], v[232:233]
	v_pk_mul_f32 v[112:113], v[112:113], v[230:231]
	v_pk_mul_f32 v[114:115], v[114:115], v[232:233]
	v_pk_mul_f32 v[116:117], v[116:117], v[230:231]
	v_pk_mul_f32 v[118:119], v[118:119], v[232:233]
	v_pk_mul_f32 v[120:121], v[120:121], v[230:231]
	v_pk_mul_f32 v[122:123], v[122:123], v[232:233]
	v_pk_mul_f32 v[124:125], v[124:125], v[230:231]
	v_pk_mul_f32 v[126:127], v[126:127], v[232:233]
	s_and_b64 vcc, exec, s[72:73]
	s_cbranch_vccz .Lqkv2_plain1
	v_mul_f32_e32 v246, v96, v96
	v_mul_f32_e32 v247, v97, v97
	v_mul_f32_e32 v248, v98, v98
	v_mul_f32_e32 v249, v99, v99
	v_fmac_f32_e32 v246, v100, v100
	v_fmac_f32_e32 v247, v101, v101
	v_fmac_f32_e32 v248, v102, v102
	v_fmac_f32_e32 v249, v103, v103
	v_fmac_f32_e32 v246, v104, v104
	v_fmac_f32_e32 v247, v105, v105
	v_fmac_f32_e32 v248, v106, v106
	v_fmac_f32_e32 v249, v107, v107
	v_fmac_f32_e32 v246, v108, v108
	v_fmac_f32_e32 v247, v109, v109
	v_fmac_f32_e32 v248, v110, v110
	v_fmac_f32_e32 v249, v111, v111
	v_add_f32_dpp v246, v246, v246 quad_perm:[1,0,3,2] row_mask:0xf bank_mask:0xf
	v_add_f32_dpp v247, v247, v247 quad_perm:[1,0,3,2] row_mask:0xf bank_mask:0xf
	v_add_f32_dpp v248, v248, v248 quad_perm:[1,0,3,2] row_mask:0xf bank_mask:0xf
	v_add_f32_dpp v249, v249, v249 quad_perm:[1,0,3,2] row_mask:0xf bank_mask:0xf
	v_add_f32_dpp v246, v246, v246 quad_perm:[2,3,0,1] row_mask:0xf bank_mask:0xf
	v_add_f32_dpp v247, v247, v247 quad_perm:[2,3,0,1] row_mask:0xf bank_mask:0xf
	v_add_f32_dpp v248, v248, v248 quad_perm:[2,3,0,1] row_mask:0xf bank_mask:0xf
	v_add_f32_dpp v249, v249, v249 quad_perm:[2,3,0,1] row_mask:0xf bank_mask:0xf
	v_add_f32_dpp v246, v246, v246 row_half_mirror row_mask:0xf bank_mask:0xf
	v_add_f32_dpp v247, v247, v247 row_half_mirror row_mask:0xf bank_mask:0xf
	v_add_f32_dpp v248, v248, v248 row_half_mirror row_mask:0xf bank_mask:0xf
	v_add_f32_dpp v249, v249, v249 row_half_mirror row_mask:0xf bank_mask:0xf
	v_add_f32_dpp v246, v246, v246 row_mirror row_mask:0xf bank_mask:0xf
	v_add_f32_dpp v247, v247, v247 row_mirror row_mask:0xf bank_mask:0xf
	v_add_f32_dpp v248, v248, v248 row_mirror row_mask:0xf bank_mask:0xf
	v_add_f32_dpp v249, v249, v249 row_mirror row_mask:0xf bank_mask:0xf
	v_fmaak_f32 v246, v250, v246, 0x358637bd
	v_fmaak_f32 v247, v250, v247, 0x358637bd
	v_cmp_gt_f32_e32 vcc, s33, v246
	v_cmp_gt_f32_e64 s[14:15], s33, v247
	v_mul_f32_e32 v224, 0x4b800000, v246
	v_mul_f32_e32 v225, 0x4b800000, v247
	v_cndmask_b32_e32 v246, v246, v224, vcc
	v_cndmask_b32_e64 v247, v247, v225, s[14:15]
; DI float shx(float v, int mask, int lane) { return __int_as_float(__builtin_amdgcn_ds_bpermute((lane ^ mask) << 2, __float_as_int(v))); }
; DI void epi_slab(const GemmCfg c, const f32x16 (&acc)[4], float* sW, const float* rss, const size_t row0, const int g, const int lane,
;                  float* const g_h, u16* const g_hb, float* const g_out, const int final_out) {
;     ...
;       if (c.epi == EPI_QKV) {
;         f32x4 x = v * rs;
;         float s = x[0] * x[0] + x[1] * x[1] + x[2] * x[2] + x[3] * x[3];
;         s += shx(s, 1, ln_); s += shx(s, 2, ln_); s += shx(s, 4, ln_); s += shx(s, 8, ln_);
;         if (g < c.nk_end) {
;           const float r2 = rsqrtf(s * (1.f / 64.f) + 1e-6f) * (g < 8 ? 0.125f * LOG2E : 1.f);
;           f32x4 gn = *(const f32x4*)(c.gain + (g < 8 ? 0 : 64) + (c4 & 63));
;           x = x * gn * r2;
;         }
	v_rsq_f32_e32 v246, v246
	v_rsq_f32_e32 v247, v247
	s_nop 0
	v_mul_f32_e32 v224, 0x45800000, v246
	v_mul_f32_e32 v225, 0x45800000, v247
	v_cndmask_b32_e32 v246, v246, v224, vcc
	v_cndmask_b32_e64 v247, v247, v225, s[14:15]
	v_mul_f32_e32 v246, v246, v130
	v_mul_f32_e32 v247, v247, v130
	v_fmaak_f32 v248, v250, v248, 0x358637bd
	v_fmaak_f32 v249, v250, v249, 0x358637bd
	v_cmp_gt_f32_e32 vcc, s33, v248
	v_cmp_gt_f32_e64 s[14:15], s33, v249
	v_mul_f32_e32 v224, 0x4b800000, v248
	v_mul_f32_e32 v225, 0x4b800000, v249
	v_cndmask_b32_e32 v248, v248, v224, vcc
	v_cndmask_b32_e64 v249, v249, v225, s[14:15]
	v_rsq_f32_e32 v248, v248
	v_rsq_f32_e32 v249, v249
	s_nop 0
	v_mul_f32_e32 v224, 0x45800000, v248
	v_mul_f32_e32 v225, 0x45800000, v249
	v_cndmask_b32_e32 v248, v248, v224, vcc
	v_cndmask_b32_e64 v249, v249, v225, s[14:15]
	v_mul_f32_e32 v248, v248, v130
	v_mul_f32_e32 v249, v249, v130
	v_pk_mul_f32 v[96:97], v[96:97], v[246:247]
	v_pk_mul_f32 v[98:99], v[98:99], v[248:249]
	v_pk_mul_f32 v[96:97], v[96:97], v[132:133] op_sel_hi:[1,0]
	v_pk_mul_f32 v[98:99], v[98:99], v[132:133] op_sel_hi:[1,0]
	v_pk_mul_f32 v[100:101], v[100:101], v[246:247]
	v_pk_mul_f32 v[102:103], v[102:103], v[248:249]
	v_pk_mul_f32 v[100:101], v[100:101], v[134:135] op_sel_hi:[1,0]
	v_pk_mul_f32 v[102:103], v[102:103], v[134:135] op_sel_hi:[1,0]
	v_pk_mul_f32 v[104:105], v[104:105], v[246:247]
	v_pk_mul_f32 v[106:107], v[106:107], v[248:249]
	v_pk_mul_f32 v[104:105], v[104:105], v[136:137] op_sel_hi:[1,0]
	v_pk_mul_f32 v[106:107], v[106:107], v[136:137] op_sel_hi:[1,0]
	v_pk_mul_f32 v[108:109], v[108:109], v[246:247]
	v_pk_mul_f32 v[110:111], v[110:111], v[248:249]
	v_pk_mul_f32 v[108:109], v[108:109], v[138:139] op_sel_hi:[1,0]
	v_pk_mul_f32 v[110:111], v[110:111], v[138:139] op_sel_hi:[1,0]
	v_mul_f32_e32 v246, v112, v112
	v_mul_f32_e32 v247, v113, v113
	v_mul_f32_e32 v248, v114, v114
	v_mul_f32_e32 v249, v115, v115
	v_fmac_f32_e32 v246, v116, v116
	v_fmac_f32_e32 v247, v117, v117
	v_fmac_f32_e32 v248, v118, v118
	v_fmac_f32_e32 v249, v119, v119
	v_fmac_f32_e32 v246, v120, v120
	v_fmac_f32_e32 v247, v121, v121
	v_fmac_f32_e32 v248, v122, v122
	v_fmac_f32_e32 v249, v123, v123
	v_fmac_f32_e32 v246, v124, v124
	v_fmac_f32_e32 v247, v125, v125
	v_fmac_f32_e32 v248, v126, v126
	v_fmac_f32_e32 v249, v127, v127
	v_add_f32_dpp v246, v246, v246 quad_perm:[1,0,3,2] row_mask:0xf bank_mask:0xf
	v_add_f32_dpp v247, v247, v247 quad_perm:[1,0,3,2] row_mask:0xf bank_mask:0xf
	v_add_f32_dpp v248, v248, v248 quad_perm:[1,0,3,2] row_mask:0xf bank_mask:0xf
	v_add_f32_dpp v249, v249, v249 quad_perm:[1,0,3,2] row_mask:0xf bank_mask:0xf
	v_add_f32_dpp v246, v246, v246 quad_perm:[2,3,0,1] row_mask:0xf bank_mask:0xf
	v_add_f32_dpp v247, v247, v247 quad_perm:[2,3,0,1] row_mask:0xf bank_mask:0xf
	v_add_f32_dpp v248, v248, v248 quad_perm:[2,3,0,1] row_mask:0xf bank_mask:0xf
	v_add_f32_dpp v249, v249, v249 quad_perm:[2,3,0,1] row_mask:0xf bank_mask:0xf
	v_add_f32_dpp v246, v246, v246 row_half_mirror row_mask:0xf bank_mask:0xf
	v_add_f32_dpp v247, v247, v247 row_half_mirror row_mask:0xf bank_mask:0xf
	v_add_f32_dpp v248, v248, v248 row_half_mirror row_mask:0xf bank_mask:0xf
	v_add_f32_dpp v249, v249, v249 row_half_mirror row_mask:0xf bank_mask:0xf
	v_add_f32_dpp v246, v246, v246 row_mirror row_mask:0xf bank_mask:0xf
	v_add_f32_dpp v247, v247, v247 row_mirror row_mask:0xf bank_mask:0xf
	v_add_f32_dpp v248, v248, v248 row_mirror row_mask:0xf bank_mask:0xf
	v_add_f32_dpp v249, v249, v249 row_mirror row_mask:0xf bank_mask:0xf
	v_fmaak_f32 v246, v250, v246, 0x358637bd
	v_fmaak_f32 v247, v250, v247, 0x358637bd
	v_cmp_gt_f32_e32 vcc, s33, v246
	v_cmp_gt_f32_e64 s[14:15], s33, v247
	v_mul_f32_e32 v224, 0x4b800000, v246
	v_mul_f32_e32 v225, 0x4b800000, v247
	v_cndmask_b32_e32 v246, v246, v224, vcc
	v_cndmask_b32_e64 v247, v247, v225, s[14:15]
	v_rsq_f32_e32 v246, v246
	v_rsq_f32_e32 v247, v247
	s_nop 0
	v_mul_f32_e32 v224, 0x45800000, v246
	v_mul_f32_e32 v225, 0x45800000, v247
	v_cndmask_b32_e32 v246, v246, v224, vcc
	v_cndmask_b32_e64 v247, v247, v225, s[14:15]
	v_mul_f32_e32 v246, v246, v130
	v_mul_f32_e32 v247, v247, v130
	v_fmaak_f32 v248, v250, v248, 0x358637bd
	v_fmaak_f32 v249, v250, v249, 0x358637bd
	v_cmp_gt_f32_e32 vcc, s33, v248
	v_cmp_gt_f32_e64 s[14:15], s33, v249
	v_mul_f32_e32 v224, 0x4b800000, v248
	v_mul_f32_e32 v225, 0x4b800000, v249
	v_cndmask_b32_e32 v248, v248, v224, vcc
	v_cndmask_b32_e64 v249, v249, v225, s[14:15]
	v_rsq_f32_e32 v248, v248
	v_rsq_f32_e32 v249, v249
	s_nop 0
	v_mul_f32_e32 v224, 0x45800000, v248
	v_mul_f32_e32 v225, 0x45800000, v249
	v_cndmask_b32_e32 v248, v248, v224, vcc
	v_cndmask_b32_e64 v249, v249, v225, s[14:15]
	v_mul_f32_e32 v248, v248, v130
	v_mul_f32_e32 v249, v249, v130
	v_pk_mul_f32 v[112:113], v[112:113], v[246:247]
	v_pk_mul_f32 v[114:115], v[114:115], v[248:249]
	v_pk_mul_f32 v[112:113], v[112:113], v[132:133] op_sel_hi:[1,0]
	v_pk_mul_f32 v[114:115], v[114:115], v[132:133] op_sel_hi:[1,0]
	v_pk_mul_f32 v[116:117], v[116:117], v[246:247]
	v_pk_mul_f32 v[118:119], v[118:119], v[248:249]
	v_pk_mul_f32 v[116:117], v[116:117], v[134:135] op_sel_hi:[1,0]
	v_pk_mul_f32 v[118:119], v[118:119], v[134:135] op_sel_hi:[1,0]
	v_pk_mul_f32 v[120:121], v[120:121], v[246:247]
	v_pk_mul_f32 v[122:123], v[122:123], v[248:249]
	v_pk_mul_f32 v[120:121], v[120:121], v[136:137] op_sel_hi:[1,0]
	v_pk_mul_f32 v[122:123], v[122:123], v[136:137] op_sel_hi:[1,0]
	v_pk_mul_f32 v[124:125], v[124:125], v[246:247]
	v_pk_mul_f32 v[126:127], v[126:127], v[248:249]
	v_pk_mul_f32 v[124:125], v[124:125], v[138:139] op_sel_hi:[1,0]
	v_pk_mul_f32 v[126:127], v[126:127], v[138:139] op_sel_hi:[1,0]
; DI float shx(float v, int mask, int lane) { return __int_as_float(__builtin_amdgcn_ds_bpermute((lane ^ mask) << 2, __float_as_int(v))); }
; DI int crow(int i, int hh) { return (i & 3) + 8 * (i >> 2) + 4 * hh; }
; DI void epi_slab(const GemmCfg c, const f32x16 (&acc)[4], float* sW, const float* rss, const size_t row0, const int g, const int lane,
;                  float* const g_h, u16* const g_hb, float* const g_out, const int final_out) {
;     ...
;   for (int nb = 0; nb < 4; ++nb)
; #pragma unroll
;     for (int i = 0; i < 16; ++i) sW[crow(i, hh) * 132 + nb * 32 + l31] = acc[nb][i];
;   asm volatile("s_waitcnt lgkmcnt(0)" ::: "memory");
;     ...
;       f32x4 v = *(const f32x4*)(sW + r * 132 + c4);
;       const float rs = c.use_rs ? rsqrtf(rss[r] * invK + 1e-6f) : 1.f;
;       if (c.epi == EPI_QKV) {
;         f32x4 x = v * rs;
;         float s = x[0] * x[0] + x[1] * x[1] + x[2] * x[2] + x[3] * x[3];
;         s += shx(s, 1, ln_); s += shx(s, 2, ln_); s += shx(s, 4, ln_); s += shx(s, 8, ln_);
;         if (g < c.nk_end) {
;           const float r2 = rsqrtf(s * (1.f / 64.f) + 1e-6f) * (g < 8 ? 0.125f * LOG2E : 1.f);
;           f32x4 gn = *(const f32x4*)(c.gain + (g < 8 ? 0 : 64) + (c4 & 63));
;           x = x * gn * r2;
;         }
;         *(u32x2*)(c.o16 + row * c.ldo + col) = MK2(pack2(x[0], x[1]), pack2(x[2], x[3]));
.Lqkv2_plain1:
	ds_write2_b32 v200, v96, v97 offset0:0 offset1:132
	ds_write2_b32 v201, v98, v99 offset0:0 offset1:132
	ds_write2_b32 v200, v100, v101 offset0:16 offset1:148
	ds_write2_b32 v201, v102, v103 offset0:16 offset1:148
	ds_write2_b32 v200, v104, v105 offset0:32 offset1:164
	ds_write2_b32 v201, v106, v107 offset0:32 offset1:164
	ds_write2_b32 v200, v108, v109 offset0:48 offset1:180
	ds_write2_b32 v201, v110, v111 offset0:48 offset1:180
	ds_write2_b32 v200, v112, v113 offset0:64 offset1:196
	ds_write2_b32 v201, v114, v115 offset0:64 offset1:196
	ds_write2_b32 v200, v116, v117 offset0:80 offset1:212
	ds_write2_b32 v201, v118, v119 offset0:80 offset1:212
	ds_write2_b32 v200, v120, v121 offset0:96 offset1:228
	ds_write2_b32 v201, v122, v123 offset0:96 offset1:228
	ds_write2_b32 v200, v124, v125 offset0:112 offset1:244
	ds_write2_b32 v201, v126, v127 offset0:112 offset1:244
	s_waitcnt lgkmcnt(0)
	ds_read_b128 v[64:67], v202
	ds_read_b128 v[68:71], v202 offset:1056
	ds_read_b128 v[72:75], v202 offset:2112
	ds_read_b128 v[76:79], v202 offset:3168
	ds_read_b128 v[80:83], v202 offset:4224
	ds_read_b128 v[84:87], v202 offset:5280
	ds_read_b128 v[88:91], v202 offset:6336
	ds_read_b128 v[92:95], v202 offset:7392
	ds_read_b128 v[96:99], v202 offset:8448
	s_waitcnt lgkmcnt(8)
	v_lshl_add_u64 v[206:207], v[204:205], 0, s[8:9]
	v_cvt_pk_bf16_f32 v64, v64, v65
	v_cvt_pk_bf16_f32 v65, v66, v67
	s_add_u32 s8, s8, s4
	s_addc_u32 s9, s9, 0
	global_store_dwordx2 v[206:207], v[64:65], off
	ds_read_b128 v[100:103], v202 offset:9504
	s_waitcnt lgkmcnt(8)
	v_lshl_add_u64 v[206:207], v[204:205], 0, s[8:9]
	v_cvt_pk_bf16_f32 v68, v68, v69
	v_cvt_pk_bf16_f32 v69, v70, v71
	s_add_u32 s8, s8, s4
	s_addc_u32 s9, s9, 0
	global_store_dwordx2 v[206:207], v[68:69], off
	ds_read_b128 v[104:107], v202 offset:10560
	s_waitcnt lgkmcnt(8)
	v_lshl_add_u64 v[206:207], v[204:205], 0, s[8:9]
	v_cvt_pk_bf16_f32 v72, v72, v73
	v_cvt_pk_bf16_f32 v73, v74, v75
	s_add_u32 s8, s8, s4
	s_addc_u32 s9, s9, 0
	global_store_dwordx2 v[206:207], v[72:73], off
	ds_read_b128 v[108:111], v202 offset:11616
	s_waitcnt lgkmcnt(8)
	v_lshl_add_u64 v[206:207], v[204:205], 0, s[8:9]
	v_cvt_pk_bf16_f32 v76, v76, v77
	v_cvt_pk_bf16_f32 v77, v78, v79
	s_add_u32 s8, s8, s4
	s_addc_u32 s9, s9, 0
	global_store_dwordx2 v[206:207], v[76:77], off
	ds_read_b128 v[112:115], v202 offset:12672
	s_waitcnt lgkmcnt(8)
	v_lshl_add_u64 v[206:207], v[204:205], 0, s[8:9]
	v_cvt_pk_bf16_f32 v80, v80, v81
	v_cvt_pk_bf16_f32 v81, v82, v83
	s_add_u32 s8, s8, s4
	s_addc_u32 s9, s9, 0
	global_store_dwordx2 v[206:207], v[80:81], off
	ds_read_b128 v[116:119], v202 offset:13728
	s_waitcnt lgkmcnt(8)
	v_lshl_add_u64 v[206:207], v[204:205], 0, s[8:9]
	v_cvt_pk_bf16_f32 v84, v84, v85
	v_cvt_pk_bf16_f32 v85, v86, v87
	s_add_u32 s8, s8, s4
	s_addc_u32 s9, s9, 0
	global_store_dwordx2 v[206:207], v[84:85], off
	ds_read_b128 v[120:123], v202 offset:14784
	s_waitcnt lgkmcnt(8)
	v_lshl_add_u64 v[206:207], v[204:205], 0, s[8:9]
	v_cvt_pk_bf16_f32 v88, v88, v89
	v_cvt_pk_bf16_f32 v89, v90, v91
	s_add_u32 s8, s8, s4
	s_addc_u32 s9, s9, 0
	global_store_dwordx2 v[206:207], v[88:89], off
	ds_read_b128 v[124:127], v202 offset:15840
	s_waitcnt lgkmcnt(8)
	v_lshl_add_u64 v[206:207], v[204:205], 0, s[8:9]
	v_cvt_pk_bf16_f32 v92, v92, v93
	v_cvt_pk_bf16_f32 v93, v94, v95
	s_add_u32 s8, s8, s4
	s_addc_u32 s9, s9, 0
	global_store_dwordx2 v[206:207], v[92:93], off
	s_waitcnt lgkmcnt(7)
	v_lshl_add_u64 v[206:207], v[204:205], 0, s[8:9]
	v_cvt_pk_bf16_f32 v96, v96, v97
	v_cvt_pk_bf16_f32 v97, v98, v99
	s_add_u32 s8, s8, s4
	s_addc_u32 s9, s9, 0
	global_store_dwordx2 v[206:207], v[96:97], off
	s_waitcnt lgkmcnt(6)
	v_lshl_add_u64 v[206:207], v[204:205], 0, s[8:9]
	v_cvt_pk_bf16_f32 v100, v100, v101
	v_cvt_pk_bf16_f32 v101, v102, v103
	s_add_u32 s8, s8, s4
	s_addc_u32 s9, s9, 0
	global_store_dwordx2 v[206:207], v[100:101], off
	s_waitcnt lgkmcnt(5)
	v_lshl_add_u64 v[206:207], v[204:205], 0, s[8:9]
	v_cvt_pk_bf16_f32 v104, v104, v105
	v_cvt_pk_bf16_f32 v105, v106, v107
	s_add_u32 s8, s8, s4
	s_addc_u32 s9, s9, 0
	global_store_dwordx2 v[206:207], v[104:105], off
	s_waitcnt lgkmcnt(4)
	v_lshl_add_u64 v[206:207], v[204:205], 0, s[8:9]
	v_cvt_pk_bf16_f32 v108, v108, v109
	v_cvt_pk_bf16_f32 v109, v110, v111
	s_add_u32 s8, s8, s4
	s_addc_u32 s9, s9, 0
	global_store_dwordx2 v[206:207], v[108:109], off
	s_waitcnt lgkmcnt(3)
	v_lshl_add_u64 v[206:207], v[204:205], 0, s[8:9]
	v_cvt_pk_bf16_f32 v112, v112, v113
	v_cvt_pk_bf16_f32 v113, v114, v115
	s_add_u32 s8, s8, s4
	s_addc_u32 s9, s9, 0
	global_store_dwordx2 v[206:207], v[112:113], off
	s_waitcnt lgkmcnt(2)
	v_lshl_add_u64 v[206:207], v[204:205], 0, s[8:9]
	v_cvt_pk_bf16_f32 v116, v116, v117
	v_cvt_pk_bf16_f32 v117, v118, v119
	s_add_u32 s8, s8, s4
	s_addc_u32 s9, s9, 0
	global_store_dwordx2 v[206:207], v[116:117], off
	s_waitcnt lgkmcnt(1)
	v_lshl_add_u64 v[206:207], v[204:205], 0, s[8:9]
	v_cvt_pk_bf16_f32 v120, v120, v121
	v_cvt_pk_bf16_f32 v121, v122, v123
	s_add_u32 s8, s8, s4
	s_addc_u32 s9, s9, 0
	global_store_dwordx2 v[206:207], v[120:121], off
	s_waitcnt lgkmcnt(0)
	v_lshl_add_u64 v[206:207], v[204:205], 0, s[8:9]
	v_cvt_pk_bf16_f32 v124, v124, v125
	v_cvt_pk_bf16_f32 v125, v126, v127
	s_add_u32 s8, s8, s4
	s_addc_u32 s9, s9, 0
	global_store_dwordx2 v[206:207], v[124:125], off
	v_pk_mul_f32 v[0:1], v[0:1], v[234:235]
	v_pk_mul_f32 v[2:3], v[2:3], v[236:237]
	v_pk_mul_f32 v[4:5], v[4:5], v[234:235]
	v_pk_mul_f32 v[6:7], v[6:7], v[236:237]
	v_pk_mul_f32 v[8:9], v[8:9], v[234:235]
	v_pk_mul_f32 v[10:11], v[10:11], v[236:237]
	v_pk_mul_f32 v[12:13], v[12:13], v[234:235]
	v_pk_mul_f32 v[14:15], v[14:15], v[236:237]
	v_pk_mul_f32 v[16:17], v[16:17], v[234:235]
	v_pk_mul_f32 v[18:19], v[18:19], v[236:237]
	v_pk_mul_f32 v[20:21], v[20:21], v[234:235]
	v_pk_mul_f32 v[22:23], v[22:23], v[236:237]
	v_pk_mul_f32 v[24:25], v[24:25], v[234:235]
	v_pk_mul_f32 v[26:27], v[26:27], v[236:237]
	v_pk_mul_f32 v[28:29], v[28:29], v[234:235]
	v_pk_mul_f32 v[30:31], v[30:31], v[236:237]
	s_and_b64 vcc, exec, s[72:73]
	s_cbranch_vccz .Lqkv2_plain2
; DI float shx(float v, int mask, int lane) { return __int_as_float(__builtin_amdgcn_ds_bpermute((lane ^ mask) << 2, __float_as_int(v))); }
; DI void epi_slab(const GemmCfg c, const f32x16 (&acc)[4], float* sW, const float* rss, const size_t row0, const int g, const int lane,
;                  float* const g_h, u16* const g_hb, float* const g_out, const int final_out) {
;     ...
;       if (c.epi == EPI_QKV) {
;         f32x4 x = v * rs;
;         float s = x[0] * x[0] + x[1] * x[1] + x[2] * x[2] + x[3] * x[3];
;         s += shx(s, 1, ln_); s += shx(s, 2, ln_); s += shx(s, 4, ln_); s += shx(s, 8, ln_);
;         if (g < c.nk_end) {
;           const float r2 = rsqrtf(s * (1.f / 64.f) + 1e-6f) * (g < 8 ? 0.125f * LOG2E : 1.f);
;           f32x4 gn = *(const f32x4*)(c.gain + (g < 8 ? 0 : 64) + (c4 & 63));
;           x = x * gn * r2;
;         }
	v_mul_f32_e32 v246, v0, v0
	v_mul_f32_e32 v247, v1, v1
	v_mul_f32_e32 v248, v2, v2
	v_mul_f32_e32 v249, v3, v3
	v_fmac_f32_e32 v246, v4, v4
	v_fmac_f32_e32 v247, v5, v5
	v_fmac_f32_e32 v248, v6, v6
	v_fmac_f32_e32 v249, v7, v7
	v_fmac_f32_e32 v246, v8, v8
	v_fmac_f32_e32 v247, v9, v9
	v_fmac_f32_e32 v248, v10, v10
	v_fmac_f32_e32 v249, v11, v11
	v_fmac_f32_e32 v246, v12, v12
	v_fmac_f32_e32 v247, v13, v13
	v_fmac_f32_e32 v248, v14, v14
	v_fmac_f32_e32 v249, v15, v15
	v_add_f32_dpp v246, v246, v246 quad_perm:[1,0,3,2] row_mask:0xf bank_mask:0xf
	v_add_f32_dpp v247, v247, v247 quad_perm:[1,0,3,2] row_mask:0xf bank_mask:0xf
	v_add_f32_dpp v248, v248, v248 quad_perm:[1,0,3,2] row_mask:0xf bank_mask:0xf
	v_add_f32_dpp v249, v249, v249 quad_perm:[1,0,3,2] row_mask:0xf bank_mask:0xf
	v_add_f32_dpp v246, v246, v246 quad_perm:[2,3,0,1] row_mask:0xf bank_mask:0xf
	v_add_f32_dpp v247, v247, v247 quad_perm:[2,3,0,1] row_mask:0xf bank_mask:0xf
	v_add_f32_dpp v248, v248, v248 quad_perm:[2,3,0,1] row_mask:0xf bank_mask:0xf
	v_add_f32_dpp v249, v249, v249 quad_perm:[2,3,0,1] row_mask:0xf bank_mask:0xf
	v_add_f32_dpp v246, v246, v246 row_half_mirror row_mask:0xf bank_mask:0xf
	v_add_f32_dpp v247, v247, v247 row_half_mirror row_mask:0xf bank_mask:0xf
	v_add_f32_dpp v248, v248, v248 row_half_mirror row_mask:0xf bank_mask:0xf
	v_add_f32_dpp v249, v249, v249 row_half_mirror row_mask:0xf bank_mask:0xf
	v_add_f32_dpp v246, v246, v246 row_mirror row_mask:0xf bank_mask:0xf
	v_add_f32_dpp v247, v247, v247 row_mirror row_mask:0xf bank_mask:0xf
	v_add_f32_dpp v248, v248, v248 row_mirror row_mask:0xf bank_mask:0xf
	v_add_f32_dpp v249, v249, v249 row_mirror row_mask:0xf bank_mask:0xf
	v_fmaak_f32 v246, v250, v246, 0x358637bd
	v_fmaak_f32 v247, v250, v247, 0x358637bd
	v_cmp_gt_f32_e32 vcc, s33, v246
	v_cmp_gt_f32_e64 s[14:15], s33, v247
	v_mul_f32_e32 v224, 0x4b800000, v246
	v_mul_f32_e32 v225, 0x4b800000, v247
	v_cndmask_b32_e32 v246, v246, v224, vcc
	v_cndmask_b32_e64 v247, v247, v225, s[14:15]
	v_rsq_f32_e32 v246, v246
	v_rsq_f32_e32 v247, v247
	s_nop 0
	v_mul_f32_e32 v224, 0x45800000, v246
	v_mul_f32_e32 v225, 0x45800000, v247
	v_cndmask_b32_e32 v246, v246, v224, vcc
	v_cndmask_b32_e64 v247, v247, v225, s[14:15]
	v_mul_f32_e32 v246, v246, v130
	v_mul_f32_e32 v247, v247, v130
	v_fmaak_f32 v248, v250, v248, 0x358637bd
	v_fmaak_f32 v249, v250, v249, 0x358637bd
	v_cmp_gt_f32_e32 vcc, s33, v248
	v_cmp_gt_f32_e64 s[14:15], s33, v249
	v_mul_f32_e32 v224, 0x4b800000, v248
	v_mul_f32_e32 v225, 0x4b800000, v249
	v_cndmask_b32_e32 v248, v248, v224, vcc
	v_cndmask_b32_e64 v249, v249, v225, s[14:15]
	v_rsq_f32_e32 v248, v248
	v_rsq_f32_e32 v249, v249
	s_nop 0
	v_mul_f32_e32 v224, 0x45800000, v248
	v_mul_f32_e32 v225, 0x45800000, v249
	v_cndmask_b32_e32 v248, v248, v224, vcc
	v_cndmask_b32_e64 v249, v249, v225, s[14:15]
	v_mul_f32_e32 v248, v248, v130
	v_mul_f32_e32 v249, v249, v130
	v_pk_mul_f32 v[0:1], v[0:1], v[246:247]
	v_pk_mul_f32 v[2:3], v[2:3], v[248:249]
	v_pk_mul_f32 v[0:1], v[0:1], v[132:133] op_sel_hi:[1,0]
	v_pk_mul_f32 v[2:3], v[2:3], v[132:133] op_sel_hi:[1,0]
	v_pk_mul_f32 v[4:5], v[4:5], v[246:247]
	v_pk_mul_f32 v[6:7], v[6:7], v[248:249]
	v_pk_mul_f32 v[4:5], v[4:5], v[134:135] op_sel_hi:[1,0]
	v_pk_mul_f32 v[6:7], v[6:7], v[134:135] op_sel_hi:[1,0]
	v_pk_mul_f32 v[8:9], v[8:9], v[246:247]
	v_pk_mul_f32 v[10:11], v[10:11], v[248:249]
	v_pk_mul_f32 v[8:9], v[8:9], v[136:137] op_sel_hi:[1,0]
	v_pk_mul_f32 v[10:11], v[10:11], v[136:137] op_sel_hi:[1,0]
	v_pk_mul_f32 v[12:13], v[12:13], v[246:247]
	v_pk_mul_f32 v[14:15], v[14:15], v[248:249]
	v_pk_mul_f32 v[12:13], v[12:13], v[138:139] op_sel_hi:[1,0]
	v_pk_mul_f32 v[14:15], v[14:15], v[138:139] op_sel_hi:[1,0]
	v_mul_f32_e32 v246, v16, v16
	v_mul_f32_e32 v247, v17, v17
	v_mul_f32_e32 v248, v18, v18
	v_mul_f32_e32 v249, v19, v19
	v_fmac_f32_e32 v246, v20, v20
	v_fmac_f32_e32 v247, v21, v21
	v_fmac_f32_e32 v248, v22, v22
	v_fmac_f32_e32 v249, v23, v23
	v_fmac_f32_e32 v246, v24, v24
	v_fmac_f32_e32 v247, v25, v25
	v_fmac_f32_e32 v248, v26, v26
	v_fmac_f32_e32 v249, v27, v27
	v_fmac_f32_e32 v246, v28, v28
	v_fmac_f32_e32 v247, v29, v29
	v_fmac_f32_e32 v248, v30, v30
	v_fmac_f32_e32 v249, v31, v31
	v_add_f32_dpp v246, v246, v246 quad_perm:[1,0,3,2] row_mask:0xf bank_mask:0xf
	v_add_f32_dpp v247, v247, v247 quad_perm:[1,0,3,2] row_mask:0xf bank_mask:0xf
	v_add_f32_dpp v248, v248, v248 quad_perm:[1,0,3,2] row_mask:0xf bank_mask:0xf
	v_add_f32_dpp v249, v249, v249 quad_perm:[1,0,3,2] row_mask:0xf bank_mask:0xf
	v_add_f32_dpp v246, v246, v246 quad_perm:[2,3,0,1] row_mask:0xf bank_mask:0xf
	v_add_f32_dpp v247, v247, v247 quad_perm:[2,3,0,1] row_mask:0xf bank_mask:0xf
	v_add_f32_dpp v248, v248, v248 quad_perm:[2,3,0,1] row_mask:0xf bank_mask:0xf
	v_add_f32_dpp v249, v249, v249 quad_perm:[2,3,0,1] row_mask:0xf bank_mask:0xf
	v_add_f32_dpp v246, v246, v246 row_half_mirror row_mask:0xf bank_mask:0xf
	v_add_f32_dpp v247, v247, v247 row_half_mirror row_mask:0xf bank_mask:0xf
	v_add_f32_dpp v248, v248, v248 row_half_mirror row_mask:0xf bank_mask:0xf
	v_add_f32_dpp v249, v249, v249 row_half_mirror row_mask:0xf bank_mask:0xf
	v_add_f32_dpp v246, v246, v246 row_mirror row_mask:0xf bank_mask:0xf
	v_add_f32_dpp v247, v247, v247 row_mirror row_mask:0xf bank_mask:0xf
	v_add_f32_dpp v248, v248, v248 row_mirror row_mask:0xf bank_mask:0xf
	v_add_f32_dpp v249, v249, v249 row_mirror row_mask:0xf bank_mask:0xf
	v_fmaak_f32 v246, v250, v246, 0x358637bd
	v_fmaak_f32 v247, v250, v247, 0x358637bd
	v_cmp_gt_f32_e32 vcc, s33, v246
	v_cmp_gt_f32_e64 s[14:15], s33, v247
	v_mul_f32_e32 v224, 0x4b800000, v246
	v_mul_f32_e32 v225, 0x4b800000, v247
; DI float shx(float v, int mask, int lane) { return __int_as_float(__builtin_amdgcn_ds_bpermute((lane ^ mask) << 2, __float_as_int(v))); }
; DI int crow(int i, int hh) { return (i & 3) + 8 * (i >> 2) + 4 * hh; }
; DI void epi_slab(const GemmCfg c, const f32x16 (&acc)[4], float* sW, const float* rss, const size_t row0, const int g, const int lane,
;                  float* const g_h, u16* const g_hb, float* const g_out, const int final_out) {
;     ...
;   for (int nb = 0; nb < 4; ++nb)
; #pragma unroll
;     for (int i = 0; i < 16; ++i) sW[crow(i, hh) * 132 + nb * 32 + l31] = acc[nb][i];
;   asm volatile("s_waitcnt lgkmcnt(0)" ::: "memory");
;     ...
;       if (c.epi == EPI_QKV) {
;         f32x4 x = v * rs;
;         float s = x[0] * x[0] + x[1] * x[1] + x[2] * x[2] + x[3] * x[3];
;         s += shx(s, 1, ln_); s += shx(s, 2, ln_); s += shx(s, 4, ln_); s += shx(s, 8, ln_);
;         if (g < c.nk_end) {
;           const float r2 = rsqrtf(s * (1.f / 64.f) + 1e-6f) * (g < 8 ? 0.125f * LOG2E : 1.f);
;           f32x4 gn = *(const f32x4*)(c.gain + (g < 8 ? 0 : 64) + (c4 & 63));
;           x = x * gn * r2;
;         }
	v_cndmask_b32_e32 v246, v246, v224, vcc
	v_cndmask_b32_e64 v247, v247, v225, s[14:15]
	v_rsq_f32_e32 v246, v246
	v_rsq_f32_e32 v247, v247
	s_nop 0
	v_mul_f32_e32 v224, 0x45800000, v246
	v_mul_f32_e32 v225, 0x45800000, v247
	v_cndmask_b32_e32 v246, v246, v224, vcc
	v_cndmask_b32_e64 v247, v247, v225, s[14:15]
	v_mul_f32_e32 v246, v246, v130
	v_mul_f32_e32 v247, v247, v130
	v_fmaak_f32 v248, v250, v248, 0x358637bd
	v_fmaak_f32 v249, v250, v249, 0x358637bd
	v_cmp_gt_f32_e32 vcc, s33, v248
	v_cmp_gt_f32_e64 s[14:15], s33, v249
	v_mul_f32_e32 v224, 0x4b800000, v248
	v_mul_f32_e32 v225, 0x4b800000, v249
	v_cndmask_b32_e32 v248, v248, v224, vcc
	v_cndmask_b32_e64 v249, v249, v225, s[14:15]
	v_rsq_f32_e32 v248, v248
	v_rsq_f32_e32 v249, v249
	s_nop 0
	v_mul_f32_e32 v224, 0x45800000, v248
	v_mul_f32_e32 v225, 0x45800000, v249
	v_cndmask_b32_e32 v248, v248, v224, vcc
	v_cndmask_b32_e64 v249, v249, v225, s[14:15]
	v_mul_f32_e32 v248, v248, v130
	v_mul_f32_e32 v249, v249, v130
	v_pk_mul_f32 v[16:17], v[16:17], v[246:247]
	v_pk_mul_f32 v[18:19], v[18:19], v[248:249]
	v_pk_mul_f32 v[16:17], v[16:17], v[132:133] op_sel_hi:[1,0]
	v_pk_mul_f32 v[18:19], v[18:19], v[132:133] op_sel_hi:[1,0]
	v_pk_mul_f32 v[20:21], v[20:21], v[246:247]
	v_pk_mul_f32 v[22:23], v[22:23], v[248:249]
	v_pk_mul_f32 v[20:21], v[20:21], v[134:135] op_sel_hi:[1,0]
	v_pk_mul_f32 v[22:23], v[22:23], v[134:135] op_sel_hi:[1,0]
	v_pk_mul_f32 v[24:25], v[24:25], v[246:247]
	v_pk_mul_f32 v[26:27], v[26:27], v[248:249]
	v_pk_mul_f32 v[24:25], v[24:25], v[136:137] op_sel_hi:[1,0]
	v_pk_mul_f32 v[26:27], v[26:27], v[136:137] op_sel_hi:[1,0]
	v_pk_mul_f32 v[28:29], v[28:29], v[246:247]
	v_pk_mul_f32 v[30:31], v[30:31], v[248:249]
	v_pk_mul_f32 v[28:29], v[28:29], v[138:139] op_sel_hi:[1,0]
	v_pk_mul_f32 v[30:31], v[30:31], v[138:139] op_sel_hi:[1,0]
.Lqkv2_plain2:
	ds_write2_b32 v198, v0, v1 offset0:0 offset1:132
	ds_write2_b32 v199, v2, v3 offset0:0 offset1:132
	ds_write2_b32 v198, v4, v5 offset0:16 offset1:148
	ds_write2_b32 v199, v6, v7 offset0:16 offset1:148
	ds_write2_b32 v198, v8, v9 offset0:32 offset1:164
	ds_write2_b32 v199, v10, v11 offset0:32 offset1:164
	ds_write2_b32 v198, v12, v13 offset0:48 offset1:180
	ds_write2_b32 v199, v14, v15 offset0:48 offset1:180
	ds_write2_b32 v198, v16, v17 offset0:64 offset1:196
	ds_write2_b32 v199, v18, v19 offset0:64 offset1:196
	ds_write2_b32 v198, v20, v21 offset0:80 offset1:212
	ds_write2_b32 v199, v22, v23 offset0:80 offset1:212
	ds_write2_b32 v198, v24, v25 offset0:96 offset1:228
	ds_write2_b32 v199, v26, v27 offset0:96 offset1:228
	ds_write2_b32 v198, v28, v29 offset0:112 offset1:244
	ds_write2_b32 v199, v30, v31 offset0:112 offset1:244
	v_pk_mul_f32 v[32:33], v[32:33], v[238:239]
	v_pk_mul_f32 v[34:35], v[34:35], v[240:241]
	v_pk_mul_f32 v[36:37], v[36:37], v[238:239]
	v_pk_mul_f32 v[38:39], v[38:39], v[240:241]
	v_pk_mul_f32 v[40:41], v[40:41], v[238:239]
	v_pk_mul_f32 v[42:43], v[42:43], v[240:241]
	v_pk_mul_f32 v[44:45], v[44:45], v[238:239]
	v_pk_mul_f32 v[46:47], v[46:47], v[240:241]
	v_pk_mul_f32 v[48:49], v[48:49], v[238:239]
	v_pk_mul_f32 v[50:51], v[50:51], v[240:241]
	v_pk_mul_f32 v[52:53], v[52:53], v[238:239]
	v_pk_mul_f32 v[54:55], v[54:55], v[240:241]
	v_pk_mul_f32 v[56:57], v[56:57], v[238:239]
	v_pk_mul_f32 v[58:59], v[58:59], v[240:241]
	v_pk_mul_f32 v[60:61], v[60:61], v[238:239]
	v_pk_mul_f32 v[62:63], v[62:63], v[240:241]
	s_and_b64 vcc, exec, s[72:73]
	s_cbranch_vccz .Lqkv2_plain3
	v_mul_f32_e32 v246, v32, v32
	v_mul_f32_e32 v247, v33, v33
	v_mul_f32_e32 v248, v34, v34
	v_mul_f32_e32 v249, v35, v35
	v_fmac_f32_e32 v246, v36, v36
	v_fmac_f32_e32 v247, v37, v37
	v_fmac_f32_e32 v248, v38, v38
	v_fmac_f32_e32 v249, v39, v39
	v_fmac_f32_e32 v246, v40, v40
	v_fmac_f32_e32 v247, v41, v41
	v_fmac_f32_e32 v248, v42, v42
	v_fmac_f32_e32 v249, v43, v43
	v_fmac_f32_e32 v246, v44, v44
	v_fmac_f32_e32 v247, v45, v45
	v_fmac_f32_e32 v248, v46, v46
	v_fmac_f32_e32 v249, v47, v47
	v_add_f32_dpp v246, v246, v246 quad_perm:[1,0,3,2] row_mask:0xf bank_mask:0xf
	v_add_f32_dpp v247, v247, v247 quad_perm:[1,0,3,2] row_mask:0xf bank_mask:0xf
	v_add_f32_dpp v248, v248, v248 quad_perm:[1,0,3,2] row_mask:0xf bank_mask:0xf
	v_add_f32_dpp v249, v249, v249 quad_perm:[1,0,3,2] row_mask:0xf bank_mask:0xf
	v_add_f32_dpp v246, v246, v246 quad_perm:[2,3,0,1] row_mask:0xf bank_mask:0xf
	v_add_f32_dpp v247, v247, v247 quad_perm:[2,3,0,1] row_mask:0xf bank_mask:0xf
	v_add_f32_dpp v248, v248, v248 quad_perm:[2,3,0,1] row_mask:0xf bank_mask:0xf
	v_add_f32_dpp v249, v249, v249 quad_perm:[2,3,0,1] row_mask:0xf bank_mask:0xf
	v_add_f32_dpp v246, v246, v246 row_half_mirror row_mask:0xf bank_mask:0xf
	v_add_f32_dpp v247, v247, v247 row_half_mirror row_mask:0xf bank_mask:0xf
	v_add_f32_dpp v248, v248, v248 row_half_mirror row_mask:0xf bank_mask:0xf
	v_add_f32_dpp v249, v249, v249 row_half_mirror row_mask:0xf bank_mask:0xf
	v_add_f32_dpp v246, v246, v246 row_mirror row_mask:0xf bank_mask:0xf
	v_add_f32_dpp v247, v247, v247 row_mirror row_mask:0xf bank_mask:0xf
	v_add_f32_dpp v248, v248, v248 row_mirror row_mask:0xf bank_mask:0xf
	v_add_f32_dpp v249, v249, v249 row_mirror row_mask:0xf bank_mask:0xf
	v_fmaak_f32 v246, v250, v246, 0x358637bd
	v_fmaak_f32 v247, v250, v247, 0x358637bd
	v_cmp_gt_f32_e32 vcc, s33, v246
	v_cmp_gt_f32_e64 s[14:15], s33, v247
	v_mul_f32_e32 v224, 0x4b800000, v246
	v_mul_f32_e32 v225, 0x4b800000, v247
	v_cndmask_b32_e32 v246, v246, v224, vcc
	v_cndmask_b32_e64 v247, v247, v225, s[14:15]
	v_rsq_f32_e32 v246, v246
	v_rsq_f32_e32 v247, v247
	s_nop 0
	v_mul_f32_e32 v224, 0x45800000, v246
	v_mul_f32_e32 v225, 0x45800000, v247
; DI float shx(float v, int mask, int lane) { return __int_as_float(__builtin_amdgcn_ds_bpermute((lane ^ mask) << 2, __float_as_int(v))); }
; DI void epi_slab(const GemmCfg c, const f32x16 (&acc)[4], float* sW, const float* rss, const size_t row0, const int g, const int lane,
;                  float* const g_h, u16* const g_hb, float* const g_out, const int final_out) {
;     ...
;       if (c.epi == EPI_QKV) {
;         f32x4 x = v * rs;
;         float s = x[0] * x[0] + x[1] * x[1] + x[2] * x[2] + x[3] * x[3];
;         s += shx(s, 1, ln_); s += shx(s, 2, ln_); s += shx(s, 4, ln_); s += shx(s, 8, ln_);
;         if (g < c.nk_end) {
;           const float r2 = rsqrtf(s * (1.f / 64.f) + 1e-6f) * (g < 8 ? 0.125f * LOG2E : 1.f);
;           f32x4 gn = *(const f32x4*)(c.gain + (g < 8 ? 0 : 64) + (c4 & 63));
;           x = x * gn * r2;
;         }
	v_cndmask_b32_e32 v246, v246, v224, vcc
	v_cndmask_b32_e64 v247, v247, v225, s[14:15]
	v_mul_f32_e32 v246, v246, v130
	v_mul_f32_e32 v247, v247, v130
	v_fmaak_f32 v248, v250, v248, 0x358637bd
	v_fmaak_f32 v249, v250, v249, 0x358637bd
	v_cmp_gt_f32_e32 vcc, s33, v248
	v_cmp_gt_f32_e64 s[14:15], s33, v249
	v_mul_f32_e32 v224, 0x4b800000, v248
	v_mul_f32_e32 v225, 0x4b800000, v249
	v_cndmask_b32_e32 v248, v248, v224, vcc
	v_cndmask_b32_e64 v249, v249, v225, s[14:15]
	v_rsq_f32_e32 v248, v248
	v_rsq_f32_e32 v249, v249
	s_nop 0
	v_mul_f32_e32 v224, 0x45800000, v248
	v_mul_f32_e32 v225, 0x45800000, v249
	v_cndmask_b32_e32 v248, v248, v224, vcc
	v_cndmask_b32_e64 v249, v249, v225, s[14:15]
	v_mul_f32_e32 v248, v248, v130
	v_mul_f32_e32 v249, v249, v130
	v_pk_mul_f32 v[32:33], v[32:33], v[246:247]
	v_pk_mul_f32 v[34:35], v[34:35], v[248:249]
	v_pk_mul_f32 v[32:33], v[32:33], v[132:133] op_sel_hi:[1,0]
	v_pk_mul_f32 v[34:35], v[34:35], v[132:133] op_sel_hi:[1,0]
	v_pk_mul_f32 v[36:37], v[36:37], v[246:247]
	v_pk_mul_f32 v[38:39], v[38:39], v[248:249]
	v_pk_mul_f32 v[36:37], v[36:37], v[134:135] op_sel_hi:[1,0]
	v_pk_mul_f32 v[38:39], v[38:39], v[134:135] op_sel_hi:[1,0]
	v_pk_mul_f32 v[40:41], v[40:41], v[246:247]
	v_pk_mul_f32 v[42:43], v[42:43], v[248:249]
	v_pk_mul_f32 v[40:41], v[40:41], v[136:137] op_sel_hi:[1,0]
	v_pk_mul_f32 v[42:43], v[42:43], v[136:137] op_sel_hi:[1,0]
	v_pk_mul_f32 v[44:45], v[44:45], v[246:247]
	v_pk_mul_f32 v[46:47], v[46:47], v[248:249]
	v_pk_mul_f32 v[44:45], v[44:45], v[138:139] op_sel_hi:[1,0]
	v_pk_mul_f32 v[46:47], v[46:47], v[138:139] op_sel_hi:[1,0]
	v_mul_f32_e32 v246, v48, v48
	v_mul_f32_e32 v247, v49, v49
	v_mul_f32_e32 v248, v50, v50
	v_mul_f32_e32 v249, v51, v51
	v_fmac_f32_e32 v246, v52, v52
	v_fmac_f32_e32 v247, v53, v53
	v_fmac_f32_e32 v248, v54, v54
	v_fmac_f32_e32 v249, v55, v55
	v_fmac_f32_e32 v246, v56, v56
	v_fmac_f32_e32 v247, v57, v57
	v_fmac_f32_e32 v248, v58, v58
	v_fmac_f32_e32 v249, v59, v59
	v_fmac_f32_e32 v246, v60, v60
	v_fmac_f32_e32 v247, v61, v61
	v_fmac_f32_e32 v248, v62, v62
	v_fmac_f32_e32 v249, v63, v63
	v_add_f32_dpp v246, v246, v246 quad_perm:[1,0,3,2] row_mask:0xf bank_mask:0xf
	v_add_f32_dpp v247, v247, v247 quad_perm:[1,0,3,2] row_mask:0xf bank_mask:0xf
	v_add_f32_dpp v248, v248, v248 quad_perm:[1,0,3,2] row_mask:0xf bank_mask:0xf
	v_add_f32_dpp v249, v249, v249 quad_perm:[1,0,3,2] row_mask:0xf bank_mask:0xf
	v_add_f32_dpp v246, v246, v246 quad_perm:[2,3,0,1] row_mask:0xf bank_mask:0xf
	v_add_f32_dpp v247, v247, v247 quad_perm:[2,3,0,1] row_mask:0xf bank_mask:0xf
	v_add_f32_dpp v248, v248, v248 quad_perm:[2,3,0,1] row_mask:0xf bank_mask:0xf
	v_add_f32_dpp v249, v249, v249 quad_perm:[2,3,0,1] row_mask:0xf bank_mask:0xf
	v_add_f32_dpp v246, v246, v246 row_half_mirror row_mask:0xf bank_mask:0xf
	v_add_f32_dpp v247, v247, v247 row_half_mirror row_mask:0xf bank_mask:0xf
	v_add_f32_dpp v248, v248, v248 row_half_mirror row_mask:0xf bank_mask:0xf
	v_add_f32_dpp v249, v249, v249 row_half_mirror row_mask:0xf bank_mask:0xf
	v_add_f32_dpp v246, v246, v246 row_mirror row_mask:0xf bank_mask:0xf
	v_add_f32_dpp v247, v247, v247 row_mirror row_mask:0xf bank_mask:0xf
	v_add_f32_dpp v248, v248, v248 row_mirror row_mask:0xf bank_mask:0xf
	v_add_f32_dpp v249, v249, v249 row_mirror row_mask:0xf bank_mask:0xf
	v_fmaak_f32 v246, v250, v246, 0x358637bd
	v_fmaak_f32 v247, v250, v247, 0x358637bd
	v_cmp_gt_f32_e32 vcc, s33, v246
	v_cmp_gt_f32_e64 s[14:15], s33, v247
	v_mul_f32_e32 v224, 0x4b800000, v246
	v_mul_f32_e32 v225, 0x4b800000, v247
	v_cndmask_b32_e32 v246, v246, v224, vcc
	v_cndmask_b32_e64 v247, v247, v225, s[14:15]
	v_rsq_f32_e32 v246, v246
	v_rsq_f32_e32 v247, v247
	s_nop 0
	v_mul_f32_e32 v224, 0x45800000, v246
	v_mul_f32_e32 v225, 0x45800000, v247
	v_cndmask_b32_e32 v246, v246, v224, vcc
	v_cndmask_b32_e64 v247, v247, v225, s[14:15]
	v_mul_f32_e32 v246, v246, v130
	v_mul_f32_e32 v247, v247, v130
	v_fmaak_f32 v248, v250, v248, 0x358637bd
	v_fmaak_f32 v249, v250, v249, 0x358637bd
	v_cmp_gt_f32_e32 vcc, s33, v248
	v_cmp_gt_f32_e64 s[14:15], s33, v249
	v_mul_f32_e32 v224, 0x4b800000, v248
	v_mul_f32_e32 v225, 0x4b800000, v249
	v_cndmask_b32_e32 v248, v248, v224, vcc
	v_cndmask_b32_e64 v249, v249, v225, s[14:15]
	v_rsq_f32_e32 v248, v248
	v_rsq_f32_e32 v249, v249
	s_nop 0
	v_mul_f32_e32 v224, 0x45800000, v248
	v_mul_f32_e32 v225, 0x45800000, v249
	v_cndmask_b32_e32 v248, v248, v224, vcc
	v_cndmask_b32_e64 v249, v249, v225, s[14:15]
	v_mul_f32_e32 v248, v248, v130
	v_mul_f32_e32 v249, v249, v130
	v_pk_mul_f32 v[48:49], v[48:49], v[246:247]
	v_pk_mul_f32 v[50:51], v[50:51], v[248:249]
	v_pk_mul_f32 v[48:49], v[48:49], v[132:133] op_sel_hi:[1,0]
	v_pk_mul_f32 v[50:51], v[50:51], v[132:133] op_sel_hi:[1,0]
	v_pk_mul_f32 v[52:53], v[52:53], v[246:247]
	v_pk_mul_f32 v[54:55], v[54:55], v[248:249]
	v_pk_mul_f32 v[52:53], v[52:53], v[134:135] op_sel_hi:[1,0]
	v_pk_mul_f32 v[54:55], v[54:55], v[134:135] op_sel_hi:[1,0]
	v_pk_mul_f32 v[56:57], v[56:57], v[246:247]
	v_pk_mul_f32 v[58:59], v[58:59], v[248:249]
	v_pk_mul_f32 v[56:57], v[56:57], v[136:137] op_sel_hi:[1,0]
	v_pk_mul_f32 v[58:59], v[58:59], v[136:137] op_sel_hi:[1,0]
	v_pk_mul_f32 v[60:61], v[60:61], v[246:247]
	v_pk_mul_f32 v[62:63], v[62:63], v[248:249]
	v_pk_mul_f32 v[60:61], v[60:61], v[138:139] op_sel_hi:[1,0]
	v_pk_mul_f32 v[62:63], v[62:63], v[138:139] op_sel_hi:[1,0]
; DI float shx(float v, int mask, int lane) { return __int_as_float(__builtin_amdgcn_ds_bpermute((lane ^ mask) << 2, __float_as_int(v))); }
; DI int crow(int i, int hh) { return (i & 3) + 8 * (i >> 2) + 4 * hh; }
; DI void epi_slab(const GemmCfg c, const f32x16 (&acc)[4], float* sW, const float* rss, const size_t row0, const int g, const int lane,
;                  float* const g_h, u16* const g_hb, float* const g_out, const int final_out) {
;     ...
;   for (int nb = 0; nb < 4; ++nb)
; #pragma unroll
;     for (int i = 0; i < 16; ++i) sW[crow(i, hh) * 132 + nb * 32 + l31] = acc[nb][i];
;   asm volatile("s_waitcnt lgkmcnt(0)" ::: "memory");
;     ...
;       f32x4 v = *(const f32x4*)(sW + r * 132 + c4);
;       const float rs = c.use_rs ? rsqrtf(rss[r] * invK + 1e-6f) : 1.f;
;       if (c.epi == EPI_QKV) {
;         f32x4 x = v * rs;
;         float s = x[0] * x[0] + x[1] * x[1] + x[2] * x[2] + x[3] * x[3];
;         s += shx(s, 1, ln_); s += shx(s, 2, ln_); s += shx(s, 4, ln_); s += shx(s, 8, ln_);
;         if (g < c.nk_end) {
;           const float r2 = rsqrtf(s * (1.f / 64.f) + 1e-6f) * (g < 8 ? 0.125f * LOG2E : 1.f);
;           f32x4 gn = *(const f32x4*)(c.gain + (g < 8 ? 0 : 64) + (c4 & 63));
;           x = x * gn * r2;
;         }
;         *(u32x2*)(c.o16 + row * c.ldo + col) = MK2(pack2(x[0], x[1]), pack2(x[2], x[3]));
.Lqkv2_plain3:
	ds_write2_b32 v200, v32, v33 offset0:0 offset1:132
	ds_write2_b32 v201, v34, v35 offset0:0 offset1:132
	ds_write2_b32 v200, v36, v37 offset0:16 offset1:148
	ds_write2_b32 v201, v38, v39 offset0:16 offset1:148
	ds_write2_b32 v200, v40, v41 offset0:32 offset1:164
	ds_write2_b32 v201, v42, v43 offset0:32 offset1:164
	ds_write2_b32 v200, v44, v45 offset0:48 offset1:180
	ds_write2_b32 v201, v46, v47 offset0:48 offset1:180
	ds_write2_b32 v200, v48, v49 offset0:64 offset1:196
	ds_write2_b32 v201, v50, v51 offset0:64 offset1:196
	ds_write2_b32 v200, v52, v53 offset0:80 offset1:212
	ds_write2_b32 v201, v54, v55 offset0:80 offset1:212
	ds_write2_b32 v200, v56, v57 offset0:96 offset1:228
	ds_write2_b32 v201, v58, v59 offset0:96 offset1:228
	ds_write2_b32 v200, v60, v61 offset0:112 offset1:244
	ds_write2_b32 v201, v62, v63 offset0:112 offset1:244
	s_waitcnt lgkmcnt(0)
	ds_read_b128 v[0:3], v202
	ds_read_b128 v[4:7], v202 offset:1056
	ds_read_b128 v[8:11], v202 offset:2112
	ds_read_b128 v[12:15], v202 offset:3168
	ds_read_b128 v[16:19], v202 offset:4224
	ds_read_b128 v[20:23], v202 offset:5280
	ds_read_b128 v[24:27], v202 offset:6336
	ds_read_b128 v[28:31], v202 offset:7392
	ds_read_b128 v[32:35], v202 offset:8448
	s_waitcnt lgkmcnt(8)
	v_lshl_add_u64 v[206:207], v[204:205], 0, s[8:9]
	v_cvt_pk_bf16_f32 v0, v0, v1
	v_cvt_pk_bf16_f32 v1, v2, v3
	s_add_u32 s8, s8, s4
	s_addc_u32 s9, s9, 0
	global_store_dwordx2 v[206:207], v[0:1], off
	ds_read_b128 v[36:39], v202 offset:9504
	s_waitcnt lgkmcnt(8)
	v_lshl_add_u64 v[206:207], v[204:205], 0, s[8:9]
	v_cvt_pk_bf16_f32 v4, v4, v5
	v_cvt_pk_bf16_f32 v5, v6, v7
	s_add_u32 s8, s8, s4
	s_addc_u32 s9, s9, 0
	global_store_dwordx2 v[206:207], v[4:5], off
	ds_read_b128 v[40:43], v202 offset:10560
	s_waitcnt lgkmcnt(8)
	v_lshl_add_u64 v[206:207], v[204:205], 0, s[8:9]
	v_cvt_pk_bf16_f32 v8, v8, v9
	v_cvt_pk_bf16_f32 v9, v10, v11
	s_add_u32 s8, s8, s4
	s_addc_u32 s9, s9, 0
	global_store_dwordx2 v[206:207], v[8:9], off
	ds_read_b128 v[44:47], v202 offset:11616
	s_waitcnt lgkmcnt(8)
	v_lshl_add_u64 v[206:207], v[204:205], 0, s[8:9]
	v_cvt_pk_bf16_f32 v12, v12, v13
	v_cvt_pk_bf16_f32 v13, v14, v15
	s_add_u32 s8, s8, s4
	s_addc_u32 s9, s9, 0
	global_store_dwordx2 v[206:207], v[12:13], off
	ds_read_b128 v[48:51], v202 offset:12672
	s_waitcnt lgkmcnt(8)
	v_lshl_add_u64 v[206:207], v[204:205], 0, s[8:9]
	v_cvt_pk_bf16_f32 v16, v16, v17
	v_cvt_pk_bf16_f32 v17, v18, v19
	s_add_u32 s8, s8, s4
	s_addc_u32 s9, s9, 0
	global_store_dwordx2 v[206:207], v[16:17], off
	ds_read_b128 v[52:55], v202 offset:13728
	s_waitcnt lgkmcnt(8)
	v_lshl_add_u64 v[206:207], v[204:205], 0, s[8:9]
	v_cvt_pk_bf16_f32 v20, v20, v21
	v_cvt_pk_bf16_f32 v21, v22, v23
	s_add_u32 s8, s8, s4
	s_addc_u32 s9, s9, 0
	global_store_dwordx2 v[206:207], v[20:21], off
	ds_read_b128 v[56:59], v202 offset:14784
	s_waitcnt lgkmcnt(8)
	v_lshl_add_u64 v[206:207], v[204:205], 0, s[8:9]
	v_cvt_pk_bf16_f32 v24, v24, v25
	v_cvt_pk_bf16_f32 v25, v26, v27
	s_add_u32 s8, s8, s4
	s_addc_u32 s9, s9, 0
	global_store_dwordx2 v[206:207], v[24:25], off
	ds_read_b128 v[60:63], v202 offset:15840
	s_waitcnt lgkmcnt(8)
	v_lshl_add_u64 v[206:207], v[204:205], 0, s[8:9]
	v_cvt_pk_bf16_f32 v28, v28, v29
	v_cvt_pk_bf16_f32 v29, v30, v31
	s_add_u32 s8, s8, s4
	s_addc_u32 s9, s9, 0
	global_store_dwordx2 v[206:207], v[28:29], off
	s_waitcnt lgkmcnt(7)
	v_lshl_add_u64 v[206:207], v[204:205], 0, s[8:9]
	v_cvt_pk_bf16_f32 v32, v32, v33
	v_cvt_pk_bf16_f32 v33, v34, v35
	s_add_u32 s8, s8, s4
	s_addc_u32 s9, s9, 0
	global_store_dwordx2 v[206:207], v[32:33], off
	s_waitcnt lgkmcnt(6)
	v_lshl_add_u64 v[206:207], v[204:205], 0, s[8:9]
	v_cvt_pk_bf16_f32 v36, v36, v37
	v_cvt_pk_bf16_f32 v37, v38, v39
	s_add_u32 s8, s8, s4
	s_addc_u32 s9, s9, 0
	global_store_dwordx2 v[206:207], v[36:37], off
	s_waitcnt lgkmcnt(5)
	v_lshl_add_u64 v[206:207], v[204:205], 0, s[8:9]
	v_cvt_pk_bf16_f32 v40, v40, v41
	v_cvt_pk_bf16_f32 v41, v42, v43
	s_add_u32 s8, s8, s4
	s_addc_u32 s9, s9, 0
	global_store_dwordx2 v[206:207], v[40:41], off
	s_waitcnt lgkmcnt(4)
	v_lshl_add_u64 v[206:207], v[204:205], 0, s[8:9]
	v_cvt_pk_bf16_f32 v44, v44, v45
	v_cvt_pk_bf16_f32 v45, v46, v47
	s_add_u32 s8, s8, s4
	s_addc_u32 s9, s9, 0
	global_store_dwordx2 v[206:207], v[44:45], off
	s_waitcnt lgkmcnt(3)
	v_lshl_add_u64 v[206:207], v[204:205], 0, s[8:9]
	v_cvt_pk_bf16_f32 v48, v48, v49
	v_cvt_pk_bf16_f32 v49, v50, v51
	s_add_u32 s8, s8, s4
	s_addc_u32 s9, s9, 0
	global_store_dwordx2 v[206:207], v[48:49], off
	s_waitcnt lgkmcnt(2)
	v_lshl_add_u64 v[206:207], v[204:205], 0, s[8:9]
	v_cvt_pk_bf16_f32 v52, v52, v53
	v_cvt_pk_bf16_f32 v53, v54, v55
	s_add_u32 s8, s8, s4
	s_addc_u32 s9, s9, 0
	global_store_dwordx2 v[206:207], v[52:53], off
	s_waitcnt lgkmcnt(1)
	v_lshl_add_u64 v[206:207], v[204:205], 0, s[8:9]
	v_cvt_pk_bf16_f32 v56, v56, v57
	v_cvt_pk_bf16_f32 v57, v58, v59
	s_add_u32 s8, s8, s4
	s_addc_u32 s9, s9, 0
	global_store_dwordx2 v[206:207], v[56:57], off
	s_waitcnt lgkmcnt(0)
	v_lshl_add_u64 v[206:207], v[204:205], 0, s[8:9]
	v_cvt_pk_bf16_f32 v60, v60, v61
	v_cvt_pk_bf16_f32 v61, v62, v63
	s_add_u32 s8, s8, s4
	s_addc_u32 s9, s9, 0
	global_store_dwordx2 v[206:207], v[60:61], off
	s_branch .LBB0_108
